# mode-0 GEMM epilogue: per-store-group vmcnt(0) moved into the conditional gate-load block (uniform tiles no longer serialise their stores); gdn_pre MFMA inversion batched per level
# speedup vs baseline: 1.7216x; 1.0023x over previous
; __device__ __forceinline__ unsigned pk2(float lo, float hi) { const f32x2 v = {lo, hi}; const bf16v2_t b = __builtin_convertvector(v, bf16v2_t); return __builtin_bit_cast(unsigned, b); }
;     __device__ __forceinline__ void operator()(const f32x4 (&acc)[2][2][4][2], const pg8::Unit& u, int wr, int wc, int fr, int fq) const {
;     ...
;                     for (int mm = 0; mm < 2; ++mm) {
;                         const int row = row0 + ai * 128 + (m0 + mm) * 16;
;                         const float* sp = (row < NTP ? srcP + (size_t)row * D : srcS + (size_t)(row - NTP) * D) + c0;
; #pragma unroll
;                         for (int bj = 0; bj < 2; ++bj)
; #pragma unroll
;                             for (int n = 0; n < 2; ++n) xv[mm][bj][n] = *(const f32x4*)(sp + bj * 128 + 4 * n);
;                     }
; #pragma unroll
;                     for (int mm = 0; mm < 2; ++mm) {
;                         const int row = row0 + ai * 128 + (m0 + mm) * 16;
;                         const float* gp = gate + (size_t)seq_of(row) * 6144 + c0;
; #pragma unroll
;                         for (int bj = 0; bj < 2; ++bj) {
;                             const f32x4 g0 = uni ? gU[bj][0] : *(const f32x4*)(gp + bj * 128), g1 = uni ? gU[bj][1] : *(const f32x4*)(gp + bj * 128 + 4);
;                             const f32x4 y0 = xv[mm][bj][0] + g0 * acc[ai][bj][m0 + mm][0], y1 = xv[mm][bj][1] + g1 * acc[ai][bj][m0 + mm][1];
;                             u32x4 w; w.x = pk2(y0[0], y0[1]); w.y = pk2(y0[2], y0[3]); w.z = pk2(y1[0], y1[1]); w.w = pk2(y1[2], y1[3]);
;                             *(u32x4*)(X16 + (size_t)row * XS + c0 + bj * 128) = w;
;                         }
;                     }
;                     __builtin_amdgcn_sched_barrier(0);
.LBB0_586:
	s_nop 0
	v_mov_b64_e32 v[172:173], v[104:105]
	s_and_b64 vcc, exec, s[0:1]
	v_mov_b64_e32 v[170:171], v[102:103]
	s_cbranch_vccnz .LBB0_588
	global_load_dwordx4 v[170:173], v[224:225], off offset:528
	s_waitcnt vmcnt(0)
.LBB0_588:
	s_add_i32 s20, s11, 0xffff0010
	v_pk_fma_f32 v[168:169], v[136:137], v[176:177], v[168:169]
	v_pk_fma_f32 v[166:167], v[134:135], v[174:175], v[166:167]
	v_pk_fma_f32 v[172:173], v[132:133], v[172:173], v[164:165]
	v_pk_fma_f32 v[164:165], v[130:131], v[170:171], v[162:163]
	s_lshr_b32 s20, s20, 5
	v_cvt_pk_bf16_f32 v162, v166, v167
	v_cvt_pk_bf16_f32 v163, v168, v169
	v_cvt_pk_bf16_f32 v164, v164, v165
	v_cvt_pk_bf16_f32 v165, v172, v173
	s_add_i32 s20, s20, 32
	global_store_dwordx4 v[222:223], v[162:165], off offset:256
	v_mov_b64_e32 v[168:169], v[120:121]
	s_and_b64 vcc, exec, s[0:1]
	v_mov_b32_e32 v162, s20
	v_mov_b32_e32 v163, s13
	v_cndmask_b32_e64 v164, v162, v163, s[2:3]
	v_readlane_b32 s2, v254, 59
	v_readlane_b32 s3, v254, 60
	v_mov_b64_e32 v[166:167], v[118:119]
	s_nop 0
	v_mov_b64_e32 v[162:163], s[2:3]
	s_movk_i32 s2, 0x6000
	v_mad_i64_i32 v[162:163], s[2:3], v164, s2, v[162:163]
	v_lshl_add_u64 v[172:173], v[212:213], 2, v[162:163]
	s_cbranch_vccnz .LBB0_590
	global_load_dwordx4 v[166:169], v[172:173], off
.LBB0_590:
	v_mov_b64_e32 v[164:165], v[116:117]
	s_and_b64 vcc, exec, s[0:1]
	v_mov_b64_e32 v[162:163], v[114:115]
	s_cbranch_vccnz .LBB0_592
	global_load_dwordx4 v[162:165], v[172:173], off offset:16
	s_waitcnt vmcnt(0)
.LBB0_592:
	v_pk_fma_f32 v[160:161], v[128:129], v[168:169], v[160:161]
	v_pk_fma_f32 v[158:159], v[126:127], v[166:167], v[158:159]
	v_lshlrev_b64 v[170:171], 12, v[218:219]
	v_pk_fma_f32 v[164:165], v[124:125], v[164:165], v[156:157]
	v_pk_fma_f32 v[156:157], v[122:123], v[162:163], v[154:155]
	v_cvt_pk_bf16_f32 v154, v158, v159
	v_cvt_pk_bf16_f32 v155, v160, v161
	v_mov_b64_e32 v[160:161], v[112:113]
	v_lshl_add_u64 v[170:171], v[216:217], 0, v[170:171]
	v_cvt_pk_bf16_f32 v156, v156, v157
	v_cvt_pk_bf16_f32 v157, v164, v165
	s_and_b64 vcc, exec, s[0:1]
	v_mov_b64_e32 v[158:159], v[110:111]
	global_store_dwordx4 v[170:171], v[154:157], off
	s_cbranch_vccnz .LBB0_594
	global_load_dwordx4 v[158:161], v[172:173], off offset:512
.LBB0_594:
	s_nop 0
	v_mov_b64_e32 v[156:157], v[104:105]
	s_and_b64 vcc, exec, s[0:1]
	v_mov_b64_e32 v[154:155], v[102:103]
	s_cbranch_vccnz .LBB0_596
	global_load_dwordx4 v[154:157], v[172:173], off offset:528
	s_waitcnt vmcnt(0)
.LBB0_596:
	v_pk_fma_f32 v[152:153], v[108:109], v[160:161], v[152:153]
	v_pk_fma_f32 v[150:151], v[106:107], v[158:159], v[150:151]
	v_pk_fma_f32 v[156:157], v[100:101], v[156:157], v[148:149]
	v_pk_fma_f32 v[148:149], v[98:99], v[154:155], v[146:147]
	v_cvt_pk_bf16_f32 v146, v150, v151
	v_cvt_pk_bf16_f32 v147, v152, v153
	v_cvt_pk_bf16_f32 v148, v148, v149
	v_cvt_pk_bf16_f32 v149, v156, v157
	global_store_dwordx4 v[170:171], v[146:149], off offset:256
	v_or_b32_e32 v224, 32, v214
	s_mov_b32 s2, 0x10000
	v_readlane_b32 s3, v254, 55
	v_readlane_b32 s20, v254, 53
	v_ashrrev_i32_e32 v225, 31, v224
	v_add_u32_e32 v146, 0xffff0020, v214
	v_cmp_gt_i32_e32 vcc, s2, v224
	v_mov_b32_e32 v150, s3
	v_readlane_b32 s21, v254, 54
	v_readlane_b32 s3, v254, 56
	v_cndmask_b32_e32 v147, 0, v225, vcc
	v_cndmask_b32_e32 v146, v146, v224, vcc
	v_mov_b32_e32 v151, s21
	v_mov_b32_e32 v152, s3
	v_mov_b32_e32 v153, s20
	v_cndmask_b32_e32 v149, v150, v151, vcc
	v_cndmask_b32_e32 v148, v152, v153, vcc
	v_lshlrev_b64 v[146:147], 12, v[146:147]
	v_lshl_add_u64 v[146:147], v[148:149], 0, v[146:147]
	v_lshl_add_u64 v[146:147], v[146:147], 0, v[220:221]
	v_or_b32_e32 v222, 48, v214
	global_load_dwordx4 v[170:173], v[146:147], off offset:16
	global_load_dwordx4 v[174:177], v[146:147], off
	global_load_dwordx4 v[162:165], v[146:147], off offset:528
	global_load_dwordx4 v[166:169], v[146:147], off offset:512
	v_ashrrev_i32_e32 v223, 31, v222
	v_add_u32_e32 v146, 0xffff0030, v214
	v_cmp_gt_i32_e64 s[2:3], s2, v222
	s_add_i32 s20, s11, 0xffff0020
	s_lshr_b32 s20, s20, 5
	v_cndmask_b32_e64 v147, 0, v223, s[2:3]
	v_cndmask_b32_e64 v146, v146, v222, s[2:3]
	v_cndmask_b32_e64 v149, v150, v151, s[2:3]
	v_cndmask_b32_e64 v148, v152, v153, s[2:3]
	v_lshlrev_b64 v[146:147], 12, v[146:147]
	v_lshl_add_u64 v[146:147], v[148:149], 0, v[146:147]
	v_lshl_add_u64 v[150:151], v[146:147], 0, v[220:221]
	global_load_dwordx4 v[154:157], v[150:151], off offset:16
	global_load_dwordx4 v[158:161], v[150:151], off
	global_load_dwordx4 v[146:149], v[150:151], off offset:528
	s_nop 0
	global_load_dwordx4 v[150:153], v[150:151], off offset:512
	s_add_i32 s20, s20, 32
	v_mov_b32_e32 v178, s20
	v_readlane_b32 s20, v254, 59
	v_mov_b32_e32 v179, s13
	v_readlane_b32 s21, v254, 60
	v_cndmask_b32_e32 v180, v178, v179, vcc
	v_mov_b64_e32 v[184:185], v[120:121]
	v_mov_b64_e32 v[178:179], s[20:21]
	s_movk_i32 s20, 0x6000
	v_mad_i64_i32 v[178:179], s[20:21], v180, s20, v[178:179]
	v_lshl_add_u64 v[226:227], v[178:179], 0, v[220:221]
	s_and_b64 vcc, exec, s[0:1]
	v_mov_b64_e32 v[182:183], v[118:119]
	s_cbranch_vccnz .LBB0_598
	global_load_dwordx4 v[182:185], v[226:227], off

; __device__ __forceinline__ unsigned pk2(float lo, float hi) { const f32x2 v = {lo, hi}; const bf16v2_t b = __builtin_convertvector(v, bf16v2_t); return __builtin_bit_cast(unsigned, b); }
;     __device__ __forceinline__ void operator()(const f32x4 (&acc)[2][2][4][2], const pg8::Unit& u, int wr, int wc, int fr, int fq) const {
;     ...
;                     for (int mm = 0; mm < 2; ++mm) {
;                         const int row = row0 + ai * 128 + (m0 + mm) * 16;
;                         const float* sp = (row < NTP ? srcP + (size_t)row * D : srcS + (size_t)(row - NTP) * D) + c0;
; #pragma unroll
;                         for (int bj = 0; bj < 2; ++bj)
; #pragma unroll
;                             for (int n = 0; n < 2; ++n) xv[mm][bj][n] = *(const f32x4*)(sp + bj * 128 + 4 * n);
;                     }
; #pragma unroll
;                     for (int mm = 0; mm < 2; ++mm) {
;                         const int row = row0 + ai * 128 + (m0 + mm) * 16;
;                         const float* gp = gate + (size_t)seq_of(row) * 6144 + c0;
; #pragma unroll
;                         for (int bj = 0; bj < 2; ++bj) {
;                             const f32x4 g0 = uni ? gU[bj][0] : *(const f32x4*)(gp + bj * 128), g1 = uni ? gU[bj][1] : *(const f32x4*)(gp + bj * 128 + 4);
;                             const f32x4 y0 = xv[mm][bj][0] + g0 * acc[ai][bj][m0 + mm][0], y1 = xv[mm][bj][1] + g1 * acc[ai][bj][m0 + mm][1];
;                             u32x4 w; w.x = pk2(y0[0], y0[1]); w.y = pk2(y0[2], y0[3]); w.z = pk2(y1[0], y1[1]); w.w = pk2(y1[2], y1[3]);
;                             *(u32x4*)(X16 + (size_t)row * XS + c0 + bj * 128) = w;
;                         }
;                     }
;                     __builtin_amdgcn_sched_barrier(0);
.LBB0_602:
	s_nop 0
	v_mov_b64_e32 v[172:173], v[104:105]
	s_and_b64 vcc, exec, s[0:1]
	v_mov_b64_e32 v[170:171], v[102:103]
	s_cbranch_vccnz .LBB0_604
	global_load_dwordx4 v[170:173], v[226:227], off offset:528
	s_waitcnt vmcnt(0)
.LBB0_604:
	s_add_i32 s20, s11, 0xffff0030
	v_pk_fma_f32 v[168:169], v[88:89], v[176:177], v[168:169]
	v_pk_fma_f32 v[166:167], v[86:87], v[174:175], v[166:167]
	v_pk_fma_f32 v[172:173], v[84:85], v[172:173], v[164:165]
	v_pk_fma_f32 v[164:165], v[82:83], v[170:171], v[162:163]
	s_lshr_b32 s20, s20, 5
	v_cvt_pk_bf16_f32 v162, v166, v167
	v_cvt_pk_bf16_f32 v163, v168, v169
	v_cvt_pk_bf16_f32 v164, v164, v165
	v_cvt_pk_bf16_f32 v165, v172, v173
	s_add_i32 s20, s20, 32
	global_store_dwordx4 v[224:225], v[162:165], off offset:256
	v_mov_b64_e32 v[168:169], v[120:121]
	s_and_b64 vcc, exec, s[0:1]
	v_mov_b32_e32 v162, s20
	v_mov_b32_e32 v163, s13
	v_cndmask_b32_e64 v164, v162, v163, s[2:3]
	v_readlane_b32 s2, v254, 59
	v_readlane_b32 s3, v254, 60
	v_mov_b64_e32 v[166:167], v[118:119]
	s_nop 0
	v_mov_b64_e32 v[162:163], s[2:3]
	s_movk_i32 s2, 0x6000
	v_mad_i64_i32 v[162:163], s[2:3], v164, s2, v[162:163]
	v_lshl_add_u64 v[172:173], v[212:213], 2, v[162:163]
	s_cbranch_vccnz .LBB0_606
	global_load_dwordx4 v[166:169], v[172:173], off

; __device__ __forceinline__ unsigned pk2(float lo, float hi) { const f32x2 v = {lo, hi}; const bf16v2_t b = __builtin_convertvector(v, bf16v2_t); return __builtin_bit_cast(unsigned, b); }
;     __device__ __forceinline__ void operator()(const f32x4 (&acc)[2][2][4][2], const pg8::Unit& u, int wr, int wc, int fr, int fq) const {
;     ...
;                     for (int mm = 0; mm < 2; ++mm) {
;                         const int row = row0 + ai * 128 + (m0 + mm) * 16;
;                         const float* sp = (row < NTP ? srcP + (size_t)row * D : srcS + (size_t)(row - NTP) * D) + c0;
; #pragma unroll
;                         for (int bj = 0; bj < 2; ++bj)
; #pragma unroll
;                             for (int n = 0; n < 2; ++n) xv[mm][bj][n] = *(const f32x4*)(sp + bj * 128 + 4 * n);
;                     }
; #pragma unroll
;                     for (int mm = 0; mm < 2; ++mm) {
;                         const int row = row0 + ai * 128 + (m0 + mm) * 16;
;                         const float* gp = gate + (size_t)seq_of(row) * 6144 + c0;
; #pragma unroll
;                         for (int bj = 0; bj < 2; ++bj) {
;                             const f32x4 g0 = uni ? gU[bj][0] : *(const f32x4*)(gp + bj * 128), g1 = uni ? gU[bj][1] : *(const f32x4*)(gp + bj * 128 + 4);
;                             const f32x4 y0 = xv[mm][bj][0] + g0 * acc[ai][bj][m0 + mm][0], y1 = xv[mm][bj][1] + g1 * acc[ai][bj][m0 + mm][1];
;                             u32x4 w; w.x = pk2(y0[0], y0[1]); w.y = pk2(y0[2], y0[3]); w.z = pk2(y1[0], y1[1]); w.w = pk2(y1[2], y1[3]);
;                             *(u32x4*)(X16 + (size_t)row * XS + c0 + bj * 128) = w;
;                         }
;                     }
;                     __builtin_amdgcn_sched_barrier(0);
.LBB0_608:
	v_pk_fma_f32 v[160:161], v[80:81], v[168:169], v[160:161]
	v_pk_fma_f32 v[158:159], v[78:79], v[166:167], v[158:159]
	v_lshlrev_b64 v[170:171], 12, v[222:223]
	v_pk_fma_f32 v[164:165], v[76:77], v[164:165], v[156:157]
	v_pk_fma_f32 v[156:157], v[74:75], v[162:163], v[154:155]
	v_cvt_pk_bf16_f32 v154, v158, v159
	v_cvt_pk_bf16_f32 v155, v160, v161
	v_mov_b64_e32 v[160:161], v[112:113]
	v_lshl_add_u64 v[170:171], v[216:217], 0, v[170:171]
	v_cvt_pk_bf16_f32 v156, v156, v157
	v_cvt_pk_bf16_f32 v157, v164, v165
	s_and_b64 vcc, exec, s[0:1]
	v_mov_b64_e32 v[158:159], v[110:111]
	global_store_dwordx4 v[170:171], v[154:157], off
	s_cbranch_vccnz .LBB0_610
	global_load_dwordx4 v[158:161], v[172:173], off offset:512

; __device__ __forceinline__ unsigned pk2(float lo, float hi) { const f32x2 v = {lo, hi}; const bf16v2_t b = __builtin_convertvector(v, bf16v2_t); return __builtin_bit_cast(unsigned, b); }
;     __device__ __forceinline__ void operator()(const f32x4 (&acc)[2][2][4][2], const pg8::Unit& u, int wr, int wc, int fr, int fq) const {
;     ...
;                 for (int am = 0; am < 4; ++am) {
;                     const int ai = am >> 1, m0 = (am & 1) * 2;
;                     f32x4 xv[2][2][2];
; #pragma unroll
;                     for (int mm = 0; mm < 2; ++mm) {
;                         const int row = row0 + ai * 128 + (m0 + mm) * 16;
;                         const float* sp = (row < NTP ? srcP + (size_t)row * D : srcS + (size_t)(row - NTP) * D) + c0;
; #pragma unroll
;                         for (int bj = 0; bj < 2; ++bj)
; #pragma unroll
;                             for (int n = 0; n < 2; ++n) xv[mm][bj][n] = *(const f32x4*)(sp + bj * 128 + 4 * n);
;                     }
; #pragma unroll
;                     for (int mm = 0; mm < 2; ++mm) {
;                         const int row = row0 + ai * 128 + (m0 + mm) * 16;
;                         const float* gp = gate + (size_t)seq_of(row) * 6144 + c0;
; #pragma unroll
;                         for (int bj = 0; bj < 2; ++bj) {
;                             const f32x4 g0 = uni ? gU[bj][0] : *(const f32x4*)(gp + bj * 128), g1 = uni ? gU[bj][1] : *(const f32x4*)(gp + bj * 128 + 4);
;                             const f32x4 y0 = xv[mm][bj][0] + g0 * acc[ai][bj][m0 + mm][0], y1 = xv[mm][bj][1] + g1 * acc[ai][bj][m0 + mm][1];
;                             u32x4 w; w.x = pk2(y0[0], y0[1]); w.y = pk2(y0[2], y0[3]); w.z = pk2(y1[0], y1[1]); w.w = pk2(y1[2], y1[3]);
;                             *(u32x4*)(X16 + (size_t)row * XS + c0 + bj * 128) = w;
;                         }
;                     }
;                     __builtin_amdgcn_sched_barrier(0);
.LBB0_612:
	v_pk_fma_f32 v[152:153], v[72:73], v[160:161], v[152:153]
	v_pk_fma_f32 v[150:151], v[70:71], v[158:159], v[150:151]
	v_pk_fma_f32 v[156:157], v[68:69], v[156:157], v[148:149]
	v_pk_fma_f32 v[148:149], v[66:67], v[154:155], v[146:147]
	v_cvt_pk_bf16_f32 v146, v150, v151
	v_cvt_pk_bf16_f32 v147, v152, v153
	v_cvt_pk_bf16_f32 v148, v148, v149
	v_cvt_pk_bf16_f32 v149, v156, v157
	global_store_dwordx4 v[170:171], v[146:149], off offset:256
	s_mov_b32 s2, 0xff80
	v_cmp_gt_i32_e32 vcc, s2, v214
	v_readlane_b32 s2, v254, 55
	v_add_u32_e32 v224, 0x80, v214
	v_ashrrev_i32_e32 v225, 31, v224
	v_mov_b32_e32 v150, s2
	v_readlane_b32 s2, v254, 53
	v_readlane_b32 s3, v254, 54
	v_add_u32_e32 v146, 0xffff0080, v214
	v_cndmask_b32_e32 v147, 0, v225, vcc
	v_mov_b32_e32 v151, s3
	v_readlane_b32 s3, v254, 56
	v_cndmask_b32_e32 v146, v146, v224, vcc
	v_mov_b32_e32 v153, s2
	v_mov_b32_e32 v152, s3
	v_cndmask_b32_e32 v149, v150, v151, vcc
	v_cndmask_b32_e32 v148, v152, v153, vcc
	v_lshlrev_b64 v[146:147], 12, v[146:147]
	v_lshl_add_u64 v[146:147], v[148:149], 0, v[146:147]
	v_lshl_add_u64 v[146:147], v[146:147], 0, v[220:221]
	v_add_u32_e32 v222, 0x90, v214
	s_mov_b32 s2, 0xff70
	global_load_dwordx4 v[170:173], v[146:147], off offset:16
	global_load_dwordx4 v[174:177], v[146:147], off
	global_load_dwordx4 v[162:165], v[146:147], off offset:528
	global_load_dwordx4 v[166:169], v[146:147], off offset:512
	v_ashrrev_i32_e32 v223, 31, v222
	v_add_u32_e32 v146, 0xffff0090, v214
	v_cmp_gt_i32_e64 s[2:3], s2, v214
	s_add_i32 s13, s11, 0xffff0080
	s_lshr_b32 s13, s13, 5
	v_cndmask_b32_e64 v147, 0, v223, s[2:3]
	v_cndmask_b32_e64 v146, v146, v222, s[2:3]
	v_cndmask_b32_e64 v149, v150, v151, s[2:3]
	v_cndmask_b32_e64 v148, v152, v153, s[2:3]
	v_lshlrev_b64 v[146:147], 12, v[146:147]
	v_lshl_add_u64 v[146:147], v[148:149], 0, v[146:147]
	v_lshl_add_u64 v[150:151], v[146:147], 0, v[220:221]
	global_load_dwordx4 v[154:157], v[150:151], off offset:16
	global_load_dwordx4 v[158:161], v[150:151], off
	global_load_dwordx4 v[146:149], v[150:151], off offset:528
	s_nop 0
	global_load_dwordx4 v[150:153], v[150:151], off offset:512
	s_add_i32 s13, s13, 32
	v_readlane_b32 s20, v254, 59
	v_ashrrev_i32_e32 v228, 11, v224
	v_mov_b32_e32 v178, s13
	v_readlane_b32 s21, v254, 60
	v_cndmask_b32_e32 v180, v178, v228, vcc
	s_movk_i32 s13, 0x6000
	v_mov_b64_e32 v[178:179], s[20:21]
	v_mad_i64_i32 v[178:179], s[20:21], v180, s13, v[178:179]
	v_mov_b64_e32 v[184:185], v[120:121]
	v_lshl_add_u64 v[226:227], v[178:179], 0, v[220:221]
	s_and_b64 vcc, exec, s[0:1]
	v_mov_b64_e32 v[182:183], v[118:119]
	s_cbranch_vccnz .LBB0_614
	global_load_dwordx4 v[182:185], v[226:227], off

; __device__ __forceinline__ unsigned pk2(float lo, float hi) { const f32x2 v = {lo, hi}; const bf16v2_t b = __builtin_convertvector(v, bf16v2_t); return __builtin_bit_cast(unsigned, b); }
;     __device__ __forceinline__ void operator()(const f32x4 (&acc)[2][2][4][2], const pg8::Unit& u, int wr, int wc, int fr, int fq) const {
;     ...
;                     for (int mm = 0; mm < 2; ++mm) {
;                         const int row = row0 + ai * 128 + (m0 + mm) * 16;
;                         const float* sp = (row < NTP ? srcP + (size_t)row * D : srcS + (size_t)(row - NTP) * D) + c0;
; #pragma unroll
;                         for (int bj = 0; bj < 2; ++bj)
; #pragma unroll
;                             for (int n = 0; n < 2; ++n) xv[mm][bj][n] = *(const f32x4*)(sp + bj * 128 + 4 * n);
;                     }
; #pragma unroll
;                     for (int mm = 0; mm < 2; ++mm) {
;                         const int row = row0 + ai * 128 + (m0 + mm) * 16;
;                         const float* gp = gate + (size_t)seq_of(row) * 6144 + c0;
; #pragma unroll
;                         for (int bj = 0; bj < 2; ++bj) {
;                             const f32x4 g0 = uni ? gU[bj][0] : *(const f32x4*)(gp + bj * 128), g1 = uni ? gU[bj][1] : *(const f32x4*)(gp + bj * 128 + 4);
;                             const f32x4 y0 = xv[mm][bj][0] + g0 * acc[ai][bj][m0 + mm][0], y1 = xv[mm][bj][1] + g1 * acc[ai][bj][m0 + mm][1];
;                             u32x4 w; w.x = pk2(y0[0], y0[1]); w.y = pk2(y0[2], y0[3]); w.z = pk2(y1[0], y1[1]); w.w = pk2(y1[2], y1[3]);
;                             *(u32x4*)(X16 + (size_t)row * XS + c0 + bj * 128) = w;
;                         }
;                     }
;                     __builtin_amdgcn_sched_barrier(0);
.LBB0_620:
	s_add_i32 s13, s11, 0xffff0090
	v_pk_fma_f32 v[168:169], v[56:57], v[176:177], v[168:169]
	v_pk_fma_f32 v[166:167], v[54:55], v[174:175], v[166:167]
	v_pk_fma_f32 v[172:173], v[52:53], v[172:173], v[164:165]
	v_pk_fma_f32 v[164:165], v[50:51], v[170:171], v[162:163]
	s_lshr_b32 s13, s13, 5
	v_cvt_pk_bf16_f32 v162, v166, v167
	v_cvt_pk_bf16_f32 v163, v168, v169
	v_cvt_pk_bf16_f32 v164, v164, v165
	v_cvt_pk_bf16_f32 v165, v172, v173
	s_add_i32 s13, s13, 32
	global_store_dwordx4 v[224:225], v[162:165], off offset:256
	v_mov_b64_e32 v[168:169], v[120:121]
	s_and_b64 vcc, exec, s[0:1]
	v_mov_b32_e32 v162, s13
	v_cndmask_b32_e64 v164, v162, v228, s[2:3]
	v_readlane_b32 s2, v254, 59
	v_readlane_b32 s3, v254, 60
	v_mov_b64_e32 v[166:167], v[118:119]
	s_nop 0
	v_mov_b64_e32 v[162:163], s[2:3]
	s_movk_i32 s2, 0x6000
	v_mad_i64_i32 v[162:163], s[2:3], v164, s2, v[162:163]
	v_lshl_add_u64 v[172:173], v[212:213], 2, v[162:163]
	s_cbranch_vccnz .LBB0_622
	global_load_dwordx4 v[166:169], v[172:173], off

; __device__ __forceinline__ unsigned pk2(float lo, float hi) { const f32x2 v = {lo, hi}; const bf16v2_t b = __builtin_convertvector(v, bf16v2_t); return __builtin_bit_cast(unsigned, b); }
;     __device__ __forceinline__ void operator()(const f32x4 (&acc)[2][2][4][2], const pg8::Unit& u, int wr, int wc, int fr, int fq) const {
;     ...
;                     for (int mm = 0; mm < 2; ++mm) {
;                         const int row = row0 + ai * 128 + (m0 + mm) * 16;
;                         const float* sp = (row < NTP ? srcP + (size_t)row * D : srcS + (size_t)(row - NTP) * D) + c0;
; #pragma unroll
;                         for (int bj = 0; bj < 2; ++bj)
; #pragma unroll
;                             for (int n = 0; n < 2; ++n) xv[mm][bj][n] = *(const f32x4*)(sp + bj * 128 + 4 * n);
;                     }
; #pragma unroll
;                     for (int mm = 0; mm < 2; ++mm) {
;                         const int row = row0 + ai * 128 + (m0 + mm) * 16;
;                         const float* gp = gate + (size_t)seq_of(row) * 6144 + c0;
; #pragma unroll
;                         for (int bj = 0; bj < 2; ++bj) {
;                             const f32x4 g0 = uni ? gU[bj][0] : *(const f32x4*)(gp + bj * 128), g1 = uni ? gU[bj][1] : *(const f32x4*)(gp + bj * 128 + 4);
;                             const f32x4 y0 = xv[mm][bj][0] + g0 * acc[ai][bj][m0 + mm][0], y1 = xv[mm][bj][1] + g1 * acc[ai][bj][m0 + mm][1];
;                             u32x4 w; w.x = pk2(y0[0], y0[1]); w.y = pk2(y0[2], y0[3]); w.z = pk2(y1[0], y1[1]); w.w = pk2(y1[2], y1[3]);
;                             *(u32x4*)(X16 + (size_t)row * XS + c0 + bj * 128) = w;
;                         }
;                     }
;                     __builtin_amdgcn_sched_barrier(0);
.LBB0_624:
	v_pk_fma_f32 v[160:161], v[48:49], v[168:169], v[160:161]
	v_pk_fma_f32 v[158:159], v[46:47], v[166:167], v[158:159]
	v_lshlrev_b64 v[170:171], 12, v[222:223]
	v_pk_fma_f32 v[164:165], v[44:45], v[164:165], v[156:157]
	v_pk_fma_f32 v[156:157], v[42:43], v[162:163], v[154:155]
	v_cvt_pk_bf16_f32 v154, v158, v159
	v_cvt_pk_bf16_f32 v155, v160, v161
	v_mov_b64_e32 v[160:161], v[112:113]
	v_lshl_add_u64 v[170:171], v[216:217], 0, v[170:171]
	v_cvt_pk_bf16_f32 v156, v156, v157
	v_cvt_pk_bf16_f32 v157, v164, v165
	s_and_b64 vcc, exec, s[0:1]
	v_mov_b64_e32 v[158:159], v[110:111]
	global_store_dwordx4 v[170:171], v[154:157], off
	s_cbranch_vccnz .LBB0_626
	global_load_dwordx4 v[158:161], v[172:173], off offset:512

; __device__ __forceinline__ unsigned pk2(float lo, float hi) { const f32x2 v = {lo, hi}; const bf16v2_t b = __builtin_convertvector(v, bf16v2_t); return __builtin_bit_cast(unsigned, b); }
;     __device__ __forceinline__ void operator()(const f32x4 (&acc)[2][2][4][2], const pg8::Unit& u, int wr, int wc, int fr, int fq) const {
;     ...
;                 for (int am = 0; am < 4; ++am) {
;                     const int ai = am >> 1, m0 = (am & 1) * 2;
;                     f32x4 xv[2][2][2];
; #pragma unroll
;                     for (int mm = 0; mm < 2; ++mm) {
;                         const int row = row0 + ai * 128 + (m0 + mm) * 16;
;                         const float* sp = (row < NTP ? srcP + (size_t)row * D : srcS + (size_t)(row - NTP) * D) + c0;
; #pragma unroll
;                         for (int bj = 0; bj < 2; ++bj)
; #pragma unroll
;                             for (int n = 0; n < 2; ++n) xv[mm][bj][n] = *(const f32x4*)(sp + bj * 128 + 4 * n);
;                     }
; #pragma unroll
;                     for (int mm = 0; mm < 2; ++mm) {
;                         const int row = row0 + ai * 128 + (m0 + mm) * 16;
;                         const float* gp = gate + (size_t)seq_of(row) * 6144 + c0;
; #pragma unroll
;                         for (int bj = 0; bj < 2; ++bj) {
;                             const f32x4 g0 = uni ? gU[bj][0] : *(const f32x4*)(gp + bj * 128), g1 = uni ? gU[bj][1] : *(const f32x4*)(gp + bj * 128 + 4);
;                             const f32x4 y0 = xv[mm][bj][0] + g0 * acc[ai][bj][m0 + mm][0], y1 = xv[mm][bj][1] + g1 * acc[ai][bj][m0 + mm][1];
;                             u32x4 w; w.x = pk2(y0[0], y0[1]); w.y = pk2(y0[2], y0[3]); w.z = pk2(y1[0], y1[1]); w.w = pk2(y1[2], y1[3]);
;                             *(u32x4*)(X16 + (size_t)row * XS + c0 + bj * 128) = w;
;                         }
;                     }
;                     __builtin_amdgcn_sched_barrier(0);
.LBB0_628:
	v_pk_fma_f32 v[152:153], v[40:41], v[160:161], v[152:153]
	v_pk_fma_f32 v[150:151], v[38:39], v[158:159], v[150:151]
	v_pk_fma_f32 v[156:157], v[36:37], v[156:157], v[148:149]
	v_pk_fma_f32 v[148:149], v[34:35], v[154:155], v[146:147]
	v_cvt_pk_bf16_f32 v146, v150, v151
	v_cvt_pk_bf16_f32 v147, v152, v153
	v_cvt_pk_bf16_f32 v148, v148, v149
	v_cvt_pk_bf16_f32 v149, v156, v157
	global_store_dwordx4 v[170:171], v[146:149], off offset:256
	s_mov_b32 s2, 0xff60
	v_cmp_gt_i32_e32 vcc, s2, v214
	v_readlane_b32 s2, v254, 55
	v_add_u32_e32 v224, 0xa0, v214
	v_ashrrev_i32_e32 v225, 31, v224
	v_mov_b32_e32 v150, s2
	v_readlane_b32 s2, v254, 53
	v_readlane_b32 s3, v254, 54
	v_add_u32_e32 v146, 0xffff00a0, v214
	v_cndmask_b32_e32 v147, 0, v225, vcc
	v_mov_b32_e32 v151, s3
	v_readlane_b32 s3, v254, 56
	v_cndmask_b32_e32 v146, v146, v224, vcc
	v_mov_b32_e32 v153, s2
	v_mov_b32_e32 v152, s3
	v_cndmask_b32_e32 v149, v150, v151, vcc
	v_cndmask_b32_e32 v148, v152, v153, vcc
	v_lshlrev_b64 v[146:147], 12, v[146:147]
	v_lshl_add_u64 v[146:147], v[148:149], 0, v[146:147]
	v_lshl_add_u64 v[146:147], v[146:147], 0, v[220:221]
	v_add_u32_e32 v222, 0xb0, v214
	s_mov_b32 s2, 0xff50
	global_load_dwordx4 v[170:173], v[146:147], off offset:16
	global_load_dwordx4 v[174:177], v[146:147], off
	global_load_dwordx4 v[162:165], v[146:147], off offset:528
	global_load_dwordx4 v[166:169], v[146:147], off offset:512
	v_ashrrev_i32_e32 v223, 31, v222
	v_add_u32_e32 v146, 0xffff00b0, v214
	v_cmp_gt_i32_e64 s[2:3], s2, v214
	s_add_i32 s13, s11, 0xffff00a0
	s_lshr_b32 s13, s13, 5
	v_cndmask_b32_e64 v147, 0, v223, s[2:3]
	v_cndmask_b32_e64 v146, v146, v222, s[2:3]
	v_cndmask_b32_e64 v149, v150, v151, s[2:3]
	v_cndmask_b32_e64 v148, v152, v153, s[2:3]
	v_lshlrev_b64 v[146:147], 12, v[146:147]
	v_lshl_add_u64 v[146:147], v[148:149], 0, v[146:147]
	v_lshl_add_u64 v[150:151], v[146:147], 0, v[220:221]
	global_load_dwordx4 v[154:157], v[150:151], off offset:16
	global_load_dwordx4 v[158:161], v[150:151], off
	global_load_dwordx4 v[146:149], v[150:151], off offset:528
	s_nop 0
	global_load_dwordx4 v[150:153], v[150:151], off offset:512
	s_add_i32 s13, s13, 32
	v_readlane_b32 s20, v254, 59
	v_mov_b32_e32 v178, s13
	v_readlane_b32 s21, v254, 60
	v_cndmask_b32_e32 v180, v178, v228, vcc
	s_movk_i32 s13, 0x6000
	v_mov_b64_e32 v[178:179], s[20:21]
	v_mad_i64_i32 v[178:179], s[20:21], v180, s13, v[178:179]
	v_mov_b64_e32 v[184:185], v[120:121]
	v_lshl_add_u64 v[226:227], v[178:179], 0, v[220:221]
	s_and_b64 vcc, exec, s[0:1]
	v_mov_b64_e32 v[182:183], v[118:119]
	s_cbranch_vccnz .LBB0_630
	global_load_dwordx4 v[182:185], v[226:227], off

; __device__ __forceinline__ unsigned pk2(float lo, float hi) { const f32x2 v = {lo, hi}; const bf16v2_t b = __builtin_convertvector(v, bf16v2_t); return __builtin_bit_cast(unsigned, b); }
;     __device__ __forceinline__ void operator()(const f32x4 (&acc)[2][2][4][2], const pg8::Unit& u, int wr, int wc, int fr, int fq) const {
;     ...
;                     for (int mm = 0; mm < 2; ++mm) {
;                         const int row = row0 + ai * 128 + (m0 + mm) * 16;
;                         const float* sp = (row < NTP ? srcP + (size_t)row * D : srcS + (size_t)(row - NTP) * D) + c0;
; #pragma unroll
;                         for (int bj = 0; bj < 2; ++bj)
; #pragma unroll
;                             for (int n = 0; n < 2; ++n) xv[mm][bj][n] = *(const f32x4*)(sp + bj * 128 + 4 * n);
;                     }
; #pragma unroll
;                     for (int mm = 0; mm < 2; ++mm) {
;                         const int row = row0 + ai * 128 + (m0 + mm) * 16;
;                         const float* gp = gate + (size_t)seq_of(row) * 6144 + c0;
; #pragma unroll
;                         for (int bj = 0; bj < 2; ++bj) {
;                             const f32x4 g0 = uni ? gU[bj][0] : *(const f32x4*)(gp + bj * 128), g1 = uni ? gU[bj][1] : *(const f32x4*)(gp + bj * 128 + 4);
;                             const f32x4 y0 = xv[mm][bj][0] + g0 * acc[ai][bj][m0 + mm][0], y1 = xv[mm][bj][1] + g1 * acc[ai][bj][m0 + mm][1];
;                             u32x4 w; w.x = pk2(y0[0], y0[1]); w.y = pk2(y0[2], y0[3]); w.z = pk2(y1[0], y1[1]); w.w = pk2(y1[2], y1[3]);
;                             *(u32x4*)(X16 + (size_t)row * XS + c0 + bj * 128) = w;
;                         }
;                     }
;                     __builtin_amdgcn_sched_barrier(0);
.LBB0_636:
	s_add_i32 s13, s11, 0xffff00b0
	v_pk_fma_f32 v[168:169], v[24:25], v[176:177], v[168:169]
	v_pk_fma_f32 v[166:167], v[22:23], v[174:175], v[166:167]
	v_pk_fma_f32 v[172:173], v[20:21], v[172:173], v[164:165]
	v_pk_fma_f32 v[164:165], v[18:19], v[170:171], v[162:163]
	s_lshr_b32 s13, s13, 5
	v_cvt_pk_bf16_f32 v162, v166, v167
	v_cvt_pk_bf16_f32 v163, v168, v169
	v_cvt_pk_bf16_f32 v164, v164, v165
	v_cvt_pk_bf16_f32 v165, v172, v173
	s_add_i32 s13, s13, 32
	global_store_dwordx4 v[220:221], v[162:165], off offset:256
	v_mov_b64_e32 v[168:169], v[120:121]
	s_and_b64 vcc, exec, s[0:1]
	v_mov_b32_e32 v162, s13
	v_cndmask_b32_e64 v164, v162, v228, s[2:3]
	v_readlane_b32 s2, v254, 59
	v_readlane_b32 s3, v254, 60
	v_mov_b64_e32 v[166:167], v[118:119]
	s_nop 0
	v_mov_b64_e32 v[162:163], s[2:3]
	s_movk_i32 s2, 0x6000
	v_mad_i64_i32 v[162:163], s[2:3], v164, s2, v[162:163]
	v_lshl_add_u64 v[172:173], v[212:213], 2, v[162:163]
	s_cbranch_vccnz .LBB0_638
	global_load_dwordx4 v[166:169], v[172:173], off

; __device__ __forceinline__ unsigned pk2(float lo, float hi) { const f32x2 v = {lo, hi}; const bf16v2_t b = __builtin_convertvector(v, bf16v2_t); return __builtin_bit_cast(unsigned, b); }
;     __device__ __forceinline__ void operator()(const f32x4 (&acc)[2][2][4][2], const pg8::Unit& u, int wr, int wc, int fr, int fq) const {
;     ...
;                     for (int mm = 0; mm < 2; ++mm) {
;                         const int row = row0 + ai * 128 + (m0 + mm) * 16;
;                         const float* sp = (row < NTP ? srcP + (size_t)row * D : srcS + (size_t)(row - NTP) * D) + c0;
; #pragma unroll
;                         for (int bj = 0; bj < 2; ++bj)
; #pragma unroll
;                             for (int n = 0; n < 2; ++n) xv[mm][bj][n] = *(const f32x4*)(sp + bj * 128 + 4 * n);
;                     }
; #pragma unroll
;                     for (int mm = 0; mm < 2; ++mm) {
;                         const int row = row0 + ai * 128 + (m0 + mm) * 16;
;                         const float* gp = gate + (size_t)seq_of(row) * 6144 + c0;
; #pragma unroll
;                         for (int bj = 0; bj < 2; ++bj) {
;                             const f32x4 g0 = uni ? gU[bj][0] : *(const f32x4*)(gp + bj * 128), g1 = uni ? gU[bj][1] : *(const f32x4*)(gp + bj * 128 + 4);
;                             const f32x4 y0 = xv[mm][bj][0] + g0 * acc[ai][bj][m0 + mm][0], y1 = xv[mm][bj][1] + g1 * acc[ai][bj][m0 + mm][1];
;                             u32x4 w; w.x = pk2(y0[0], y0[1]); w.y = pk2(y0[2], y0[3]); w.z = pk2(y1[0], y1[1]); w.w = pk2(y1[2], y1[3]);
;                             *(u32x4*)(X16 + (size_t)row * XS + c0 + bj * 128) = w;
;                         }
;                     }
;                     __builtin_amdgcn_sched_barrier(0);
.LBB0_640:
	v_pk_fma_f32 v[160:161], v[16:17], v[168:169], v[160:161]
	v_pk_fma_f32 v[158:159], v[14:15], v[166:167], v[158:159]
	v_lshlrev_b64 v[170:171], 12, v[222:223]
	v_pk_fma_f32 v[164:165], v[12:13], v[164:165], v[156:157]
	v_pk_fma_f32 v[156:157], v[10:11], v[162:163], v[154:155]
	v_cvt_pk_bf16_f32 v154, v158, v159
	v_cvt_pk_bf16_f32 v155, v160, v161
	v_mov_b64_e32 v[160:161], v[112:113]
	v_lshl_add_u64 v[170:171], v[216:217], 0, v[170:171]
	v_cvt_pk_bf16_f32 v156, v156, v157
	v_cvt_pk_bf16_f32 v157, v164, v165
	s_and_b64 vcc, exec, s[0:1]
	v_mov_b64_e32 v[158:159], v[110:111]
	global_store_dwordx4 v[170:171], v[154:157], off
	s_cbranch_vccnz .LBB0_642
	global_load_dwordx4 v[158:161], v[172:173], off offset:512

; __device__ __forceinline__ unsigned pk2(float lo, float hi) { const f32x2 v = {lo, hi}; const bf16v2_t b = __builtin_convertvector(v, bf16v2_t); return __builtin_bit_cast(unsigned, b); }
;     __device__ __forceinline__ void operator()(const f32x4 (&acc)[2][2][4][2], const pg8::Unit& u, int wr, int wc, int fr, int fq) const {
;     ...
;                     for (int mm = 0; mm < 2; ++mm) {
;                         const int row = row0 + ai * 128 + (m0 + mm) * 16;
;                         const float* sp = (row < NTP ? srcP + (size_t)row * D : srcS + (size_t)(row - NTP) * D) + c0;
; #pragma unroll
;                         for (int bj = 0; bj < 2; ++bj)
; #pragma unroll
;                             for (int n = 0; n < 2; ++n) xv[mm][bj][n] = *(const f32x4*)(sp + bj * 128 + 4 * n);
;                     }
; #pragma unroll
;                     for (int mm = 0; mm < 2; ++mm) {
;                         const int row = row0 + ai * 128 + (m0 + mm) * 16;
;                         const float* gp = gate + (size_t)seq_of(row) * 6144 + c0;
; #pragma unroll
;                         for (int bj = 0; bj < 2; ++bj) {
;                             const f32x4 g0 = uni ? gU[bj][0] : *(const f32x4*)(gp + bj * 128), g1 = uni ? gU[bj][1] : *(const f32x4*)(gp + bj * 128 + 4);
;                             const f32x4 y0 = xv[mm][bj][0] + g0 * acc[ai][bj][m0 + mm][0], y1 = xv[mm][bj][1] + g1 * acc[ai][bj][m0 + mm][1];
;                             u32x4 w; w.x = pk2(y0[0], y0[1]); w.y = pk2(y0[2], y0[3]); w.z = pk2(y1[0], y1[1]); w.w = pk2(y1[2], y1[3]);
;                             *(u32x4*)(X16 + (size_t)row * XS + c0 + bj * 128) = w;
;                         }
;                     }
;                     __builtin_amdgcn_sched_barrier(0);
.LBB0_644:
	v_pk_fma_f32 v[152:153], v[8:9], v[160:161], v[152:153]
	v_pk_fma_f32 v[150:151], v[6:7], v[158:159], v[150:151]
	v_pk_fma_f32 v[156:157], v[4:5], v[156:157], v[148:149]
	v_pk_fma_f32 v[148:149], v[2:3], v[154:155], v[146:147]
	v_cvt_pk_bf16_f32 v146, v150, v151
	v_cvt_pk_bf16_f32 v147, v152, v153
	v_cvt_pk_bf16_f32 v148, v148, v149
	v_cvt_pk_bf16_f32 v149, v156, v157
	global_store_dwordx4 v[170:171], v[146:149], off offset:256
	s_branch .LBB0_711

; __device__ __forceinline__ unsigned pk2(float lo, float hi) { const f32x2 v = {lo, hi}; const bf16v2_t b = __builtin_convertvector(v, bf16v2_t); return __builtin_bit_cast(unsigned, b); }
;     __device__ __forceinline__ void operator()(const f32x4 (&acc)[2][2][4][2], const pg8::Unit& u, int wr, int wc, int fr, int fq) const {
;     ...
;                 for (int ai = 0; ai < 2; ++ai) {
;                     u32x4 xv[4][2];
; #pragma unroll
;                     for (int m = 0; m < 4; ++m)
; #pragma unroll
;                         for (int bj = 0; bj < 2; ++bj) xv[m][bj] = *(const u32x4*)(X16 + (size_t)(row0 + ai * 128 + m * 16) * XS + c0 + bj * 128);
; #pragma unroll
;                     for (int m = 0; m < 4; ++m) {
;                         const int row = row0 + ai * 128 + m * 16;
;                         const float* gp = gate + (size_t)seq_of(row) * 6144 + c0;
; #pragma unroll
;                         for (int bj = 0; bj < 2; ++bj) {
;                             const f32x4 g0 = uni ? gU[bj][0] : *(const f32x4*)(gp + bj * 128), g1 = uni ? gU[bj][1] : *(const f32x4*)(gp + bj * 128 + 4);
;                             float x[8]; unpack8(xv[m][bj], x);
;                             const f32x4 a0 = acc[ai][bj][m][0], a1 = acc[ai][bj][m][1];
;                             u32x4 w; w.x = pk2(x[0] + g0[0] * a0[0], x[1] + g0[1] * a0[1]); w.y = pk2(x[2] + g0[2] * a0[2], x[3] + g0[3] * a0[3]);
;                             w.z = pk2(x[4] + g1[0] * a1[0], x[5] + g1[1] * a1[1]); w.w = pk2(x[6] + g1[2] * a1[2], x[7] + g1[3] * a1[3]);
;                             *(u32x4*)(X16 + (size_t)row * XS + c0 + bj * 128) = w;
;                         }
;                     }
;                     __builtin_amdgcn_sched_barrier(0);
.LBB0_651:
	v_mov_b64_e32 v[140:141], v[104:105]
	s_and_b64 vcc, exec, s[0:1]
	v_mov_b64_e32 v[138:139], v[102:103]
	s_cbranch_vccnz .LBB0_653
	global_load_dwordx4 v[138:141], v[232:233], off offset:528
	s_waitcnt vmcnt(0)
.LBB0_653:
	v_lshlrev_b32_e32 v174, 16, v170
	v_and_b32_e32 v175, 0xffff0000, v170
	v_pk_fma_f32 v[134:135], v[134:135], v[142:143], v[174:175]
	v_lshlrev_b32_e32 v142, 16, v171
	v_and_b32_e32 v143, 0xffff0000, v171
	v_pk_fma_f32 v[136:137], v[136:137], v[144:145], v[142:143]
	v_cvt_pk_bf16_f32 v134, v134, v135
	v_cvt_pk_bf16_f32 v135, v136, v137
	v_lshlrev_b32_e32 v136, 16, v172
	v_and_b32_e32 v137, 0xffff0000, v172
	v_pk_fma_f32 v[130:131], v[130:131], v[138:139], v[136:137]
	s_add_i32 s3, s11, 0xffff0010
	v_cvt_pk_bf16_f32 v136, v130, v131
	v_lshlrev_b32_e32 v130, 16, v173
	v_and_b32_e32 v131, 0xffff0000, v173
	s_lshr_b32 s3, s3, 5
	v_pk_fma_f32 v[130:131], v[132:133], v[140:141], v[130:131]
	s_add_i32 s3, s3, 32
	v_readlane_b32 s18, v254, 59
	v_cvt_pk_bf16_f32 v137, v130, v131
	v_mov_b32_e32 v130, s3
	v_mov_b32_e32 v131, s2
	v_cmp_gt_i32_e32 vcc, s22, v218
	v_readlane_b32 s19, v254, 60
	s_movk_i32 s3, 0x6000
	v_cndmask_b32_e32 v132, v130, v131, vcc
	v_mov_b64_e32 v[130:131], s[18:19]
	global_store_dwordx4 v[230:231], v[134:137], off offset:256
	v_mad_i64_i32 v[130:131], s[18:19], v132, s3, v[130:131]
	s_nop 0
	v_mov_b64_e32 v[136:137], v[120:121]
	v_lshl_add_u64 v[138:139], v[212:213], 2, v[130:131]
	s_and_b64 vcc, exec, s[0:1]
	v_mov_b64_e32 v[134:135], v[118:119]
	s_cbranch_vccnz .LBB0_655
	global_load_dwordx4 v[134:137], v[138:139], off
.LBB0_655:
	v_mov_b64_e32 v[132:133], v[116:117]
	s_and_b64 vcc, exec, s[0:1]
	v_mov_b64_e32 v[130:131], v[114:115]
	s_cbranch_vccnz .LBB0_657
	global_load_dwordx4 v[130:133], v[138:139], off offset:16
	s_waitcnt vmcnt(0)
.LBB0_657:
	v_lshlrev_b32_e32 v140, 16, v166
	v_and_b32_e32 v141, 0xffff0000, v166
	v_pk_fma_f32 v[126:127], v[126:127], v[134:135], v[140:141]
	v_lshlrev_b32_e32 v134, 16, v167
	v_and_b32_e32 v135, 0xffff0000, v167
	v_pk_fma_f32 v[128:129], v[128:129], v[136:137], v[134:135]
	v_cvt_pk_bf16_f32 v126, v126, v127
	v_cvt_pk_bf16_f32 v127, v128, v129
	v_lshlrev_b32_e32 v128, 16, v168
	v_and_b32_e32 v129, 0xffff0000, v168
	v_pk_fma_f32 v[122:123], v[122:123], v[130:131], v[128:129]
	s_and_b64 vcc, exec, s[0:1]
	v_cvt_pk_bf16_f32 v128, v122, v123
	v_lshlrev_b32_e32 v122, 16, v169
	v_and_b32_e32 v123, 0xffff0000, v169
	v_pk_fma_f32 v[122:123], v[124:125], v[132:133], v[122:123]
	s_nop 0
	v_cvt_pk_bf16_f32 v129, v122, v123
	global_store_dwordx4 v[228:229], v[126:129], off
	s_nop 1
	v_mov_b64_e32 v[128:129], v[112:113]
	v_mov_b64_e32 v[126:127], v[110:111]
	s_cbranch_vccnz .LBB0_659
	global_load_dwordx4 v[126:129], v[138:139], off offset:512
.LBB0_659:
	v_mov_b64_e32 v[124:125], v[104:105]
	s_and_b64 vcc, exec, s[0:1]
	v_mov_b64_e32 v[122:123], v[102:103]
	s_cbranch_vccnz .LBB0_661
	global_load_dwordx4 v[122:125], v[138:139], off offset:528
	s_waitcnt vmcnt(0)
.LBB0_661:
	v_lshlrev_b32_e32 v130, 16, v162
	v_and_b32_e32 v131, 0xffff0000, v162
	v_pk_fma_f32 v[106:107], v[106:107], v[126:127], v[130:131]
	v_lshlrev_b32_e32 v126, 16, v163
	v_and_b32_e32 v127, 0xffff0000, v163
	v_pk_fma_f32 v[108:109], v[108:109], v[128:129], v[126:127]
	v_cvt_pk_bf16_f32 v106, v106, v107
	v_cvt_pk_bf16_f32 v107, v108, v109
	v_lshlrev_b32_e32 v108, 16, v164
	v_and_b32_e32 v109, 0xffff0000, v164
	v_pk_fma_f32 v[98:99], v[98:99], v[122:123], v[108:109]
	s_add_i32 s3, s11, 0xffff0020
	v_cvt_pk_bf16_f32 v108, v98, v99
	v_lshlrev_b32_e32 v98, 16, v165
	v_and_b32_e32 v99, 0xffff0000, v165
	s_lshr_b32 s3, s3, 5
	v_pk_fma_f32 v[98:99], v[100:101], v[124:125], v[98:99]
	s_add_i32 s3, s3, 32
	v_readlane_b32 s18, v254, 59
	v_cvt_pk_bf16_f32 v109, v98, v99
	v_mov_b32_e32 v98, s3
	v_mov_b32_e32 v99, s2
	v_cmp_gt_i32_e32 vcc, s22, v226
	v_readlane_b32 s19, v254, 60
	s_movk_i32 s3, 0x6000
	v_cndmask_b32_e32 v100, v98, v99, vcc
	v_mov_b64_e32 v[98:99], s[18:19]
	global_store_dwordx4 v[228:229], v[106:109], off offset:256
	v_mad_i64_i32 v[98:99], s[18:19], v100, s3, v[98:99]
	s_nop 0
	v_mov_b64_e32 v[106:107], v[118:119]
	v_lshl_add_u64 v[122:123], v[212:213], 2, v[98:99]
	s_and_b64 vcc, exec, s[0:1]
	v_mov_b64_e32 v[108:109], v[120:121]
	s_cbranch_vccnz .LBB0_663
	global_load_dwordx4 v[106:109], v[122:123], off
.LBB0_663:
	v_mov_b64_e32 v[98:99], v[114:115]
	s_and_b64 vcc, exec, s[0:1]
	v_mov_b64_e32 v[100:101], v[116:117]
	s_cbranch_vccnz .LBB0_665
	global_load_dwordx4 v[98:101], v[122:123], off offset:16
	s_waitcnt vmcnt(0)
.LBB0_665:
	v_lshlrev_b32_e32 v124, 16, v158
	v_and_b32_e32 v125, 0xffff0000, v158
	v_pk_fma_f32 v[94:95], v[94:95], v[106:107], v[124:125]
	v_lshlrev_b32_e32 v106, 16, v159
	v_and_b32_e32 v107, 0xffff0000, v159
	v_pk_fma_f32 v[96:97], v[96:97], v[108:109], v[106:107]
	v_cvt_pk_bf16_f32 v94, v94, v95
	v_cvt_pk_bf16_f32 v95, v96, v97
	v_lshlrev_b32_e32 v96, 16, v160
	v_and_b32_e32 v97, 0xffff0000, v160
	v_pk_fma_f32 v[90:91], v[90:91], v[98:99], v[96:97]
	s_and_b64 vcc, exec, s[0:1]
	v_cvt_pk_bf16_f32 v96, v90, v91
	v_lshlrev_b32_e32 v90, 16, v161
	v_and_b32_e32 v91, 0xffff0000, v161
	v_pk_fma_f32 v[90:91], v[92:93], v[100:101], v[90:91]
	s_nop 0
	v_cvt_pk_bf16_f32 v97, v90, v91
	global_store_dwordx4 v[224:225], v[94:97], off
	s_nop 1
	v_mov_b64_e32 v[94:95], v[110:111]
	v_mov_b64_e32 v[96:97], v[112:113]
	s_cbranch_vccnz .LBB0_667
	global_load_dwordx4 v[94:97], v[122:123], off offset:512
; __device__ __forceinline__ unsigned pk2(float lo, float hi) { const f32x2 v = {lo, hi}; const bf16v2_t b = __builtin_convertvector(v, bf16v2_t); return __builtin_bit_cast(unsigned, b); }
;     __device__ __forceinline__ void operator()(const f32x4 (&acc)[2][2][4][2], const pg8::Unit& u, int wr, int wc, int fr, int fq) const {
;     ...
;                 for (int ai = 0; ai < 2; ++ai) {
;                     u32x4 xv[4][2];
; #pragma unroll
;                     for (int m = 0; m < 4; ++m)
; #pragma unroll
;                         for (int bj = 0; bj < 2; ++bj) xv[m][bj] = *(const u32x4*)(X16 + (size_t)(row0 + ai * 128 + m * 16) * XS + c0 + bj * 128);
; #pragma unroll
;                     for (int m = 0; m < 4; ++m) {
;                         const int row = row0 + ai * 128 + m * 16;
;                         const float* gp = gate + (size_t)seq_of(row) * 6144 + c0;
; #pragma unroll
;                         for (int bj = 0; bj < 2; ++bj) {
;                             const f32x4 g0 = uni ? gU[bj][0] : *(const f32x4*)(gp + bj * 128), g1 = uni ? gU[bj][1] : *(const f32x4*)(gp + bj * 128 + 4);
;                             float x[8]; unpack8(xv[m][bj], x);
;                             const f32x4 a0 = acc[ai][bj][m][0], a1 = acc[ai][bj][m][1];
;                             u32x4 w; w.x = pk2(x[0] + g0[0] * a0[0], x[1] + g0[1] * a0[1]); w.y = pk2(x[2] + g0[2] * a0[2], x[3] + g0[3] * a0[3]);
;                             w.z = pk2(x[4] + g1[0] * a1[0], x[5] + g1[1] * a1[1]); w.w = pk2(x[6] + g1[2] * a1[2], x[7] + g1[3] * a1[3]);
;                             *(u32x4*)(X16 + (size_t)row * XS + c0 + bj * 128) = w;
;                         }
;                     }
;                     __builtin_amdgcn_sched_barrier(0);
.LBB0_667:
	v_mov_b64_e32 v[90:91], v[102:103]
	s_and_b64 vcc, exec, s[0:1]
	v_mov_b64_e32 v[92:93], v[104:105]
	s_cbranch_vccnz .LBB0_669
	global_load_dwordx4 v[90:93], v[122:123], off offset:528
	s_waitcnt vmcnt(0)
.LBB0_669:
	v_lshlrev_b32_e32 v98, 16, v154
	v_and_b32_e32 v99, 0xffff0000, v154
	v_pk_fma_f32 v[86:87], v[86:87], v[94:95], v[98:99]
	v_lshlrev_b32_e32 v94, 16, v155
	v_and_b32_e32 v95, 0xffff0000, v155
	v_pk_fma_f32 v[88:89], v[88:89], v[96:97], v[94:95]
	v_cvt_pk_bf16_f32 v86, v86, v87
	v_cvt_pk_bf16_f32 v87, v88, v89
	v_lshlrev_b32_e32 v88, 16, v156
	v_and_b32_e32 v89, 0xffff0000, v156
	v_pk_fma_f32 v[82:83], v[82:83], v[90:91], v[88:89]
	s_add_i32 s3, s11, 0xffff0030
	v_cvt_pk_bf16_f32 v88, v82, v83
	v_lshlrev_b32_e32 v82, 16, v157
	v_and_b32_e32 v83, 0xffff0000, v157
	s_lshr_b32 s3, s3, 5
	v_pk_fma_f32 v[82:83], v[84:85], v[92:93], v[82:83]
	s_add_i32 s3, s3, 32
	v_cvt_pk_bf16_f32 v89, v82, v83
	v_mov_b32_e32 v82, s3
	v_mov_b32_e32 v83, s2
	v_readlane_b32 s2, v254, 59
	v_cmp_gt_i32_e32 vcc, s22, v222
	v_readlane_b32 s3, v254, 60
	global_store_dwordx4 v[224:225], v[86:89], off offset:256
	v_cndmask_b32_e32 v84, v82, v83, vcc
	v_mov_b64_e32 v[82:83], s[2:3]
	s_movk_i32 s2, 0x6000
	v_mad_i64_i32 v[82:83], s[2:3], v84, s2, v[82:83]
	v_mov_b64_e32 v[86:87], v[118:119]
	v_lshl_add_u64 v[90:91], v[212:213], 2, v[82:83]
	s_and_b64 vcc, exec, s[0:1]
	v_mov_b64_e32 v[88:89], v[120:121]
	s_cbranch_vccnz .LBB0_671
	global_load_dwordx4 v[86:89], v[90:91], off
.LBB0_671:
	v_mov_b64_e32 v[82:83], v[114:115]
	s_and_b64 vcc, exec, s[0:1]
	v_mov_b64_e32 v[84:85], v[116:117]
	s_cbranch_vccnz .LBB0_673
	global_load_dwordx4 v[82:85], v[90:91], off offset:16
	s_waitcnt vmcnt(0)
.LBB0_673:
	v_lshlrev_b32_e32 v92, 16, v150
	v_and_b32_e32 v93, 0xffff0000, v150
	v_pk_fma_f32 v[78:79], v[78:79], v[86:87], v[92:93]
	v_lshlrev_b32_e32 v86, 16, v151
	v_and_b32_e32 v87, 0xffff0000, v151
	v_pk_fma_f32 v[80:81], v[80:81], v[88:89], v[86:87]
	v_cvt_pk_bf16_f32 v78, v78, v79
	v_cvt_pk_bf16_f32 v79, v80, v81
	v_lshlrev_b32_e32 v80, 16, v152
	v_and_b32_e32 v81, 0xffff0000, v152
	v_pk_fma_f32 v[74:75], v[74:75], v[82:83], v[80:81]
	s_and_b64 vcc, exec, s[0:1]
	v_cvt_pk_bf16_f32 v80, v74, v75
	v_lshlrev_b32_e32 v74, 16, v153
	v_and_b32_e32 v75, 0xffff0000, v153
	v_pk_fma_f32 v[74:75], v[76:77], v[84:85], v[74:75]
	s_nop 0
	v_cvt_pk_bf16_f32 v81, v74, v75
	global_store_dwordx4 v[220:221], v[78:81], off
	s_nop 1
	v_mov_b64_e32 v[78:79], v[110:111]
	v_mov_b64_e32 v[80:81], v[112:113]
	s_cbranch_vccnz .LBB0_675
	global_load_dwordx4 v[78:81], v[90:91], off offset:512
.LBB0_675:
	v_mov_b64_e32 v[74:75], v[102:103]
	s_and_b64 vcc, exec, s[0:1]
	v_mov_b64_e32 v[76:77], v[104:105]
	s_cbranch_vccnz .LBB0_677
	global_load_dwordx4 v[74:77], v[90:91], off offset:528
	s_waitcnt vmcnt(0)
.LBB0_677:
	v_lshlrev_b32_e32 v82, 16, v146
	v_and_b32_e32 v83, 0xffff0000, v146
	v_pk_fma_f32 v[70:71], v[70:71], v[78:79], v[82:83]
	v_lshlrev_b32_e32 v78, 16, v147
	v_and_b32_e32 v79, 0xffff0000, v147
	v_pk_fma_f32 v[72:73], v[72:73], v[80:81], v[78:79]
	v_cvt_pk_bf16_f32 v70, v70, v71
	v_cvt_pk_bf16_f32 v71, v72, v73
	v_lshlrev_b32_e32 v72, 16, v148
	v_and_b32_e32 v73, 0xffff0000, v148
	v_pk_fma_f32 v[66:67], v[66:67], v[74:75], v[72:73]
	s_nop 0
	v_cvt_pk_bf16_f32 v72, v66, v67
	v_lshlrev_b32_e32 v66, 16, v149
	v_and_b32_e32 v67, 0xffff0000, v149
	v_pk_fma_f32 v[66:67], v[68:69], v[76:77], v[66:67]
	s_nop 0
	v_cvt_pk_bf16_f32 v73, v66, v67
	global_store_dwordx4 v[220:221], v[70:73], off offset:256
	v_add_u32_e32 v98, 0x80, v214
	v_ashrrev_i32_e32 v99, 31, v98
	v_lshlrev_b64 v[66:67], 12, v[98:99]
	v_lshl_add_u64 v[128:129], v[216:217], 0, v[66:67]
	v_lshlrev_b64 v[66:67], 12, v[214:215]
	v_lshl_add_u64 v[66:67], v[216:217], 0, v[66:67]
	s_mov_b64 s[2:3], 0x90000
	v_lshl_add_u64 v[126:127], v[66:67], 0, s[2:3]
	s_mov_b32 s2, 0x90000
	v_add_co_u32_e32 v68, vcc, s2, v66
	s_mov_b64 s[2:3], 0xa0000
	s_nop 0
	v_addc_co_u32_e32 v69, vcc, 0, v67, vcc
	v_lshl_add_u64 v[124:125], v[66:67], 0, s[2:3]
	s_mov_b32 s2, 0xa0000
	v_add_co_u32_e32 v70, vcc, s2, v66
	s_mov_b64 s[2:3], 0xb0000
	s_nop 0
	v_addc_co_u32_e32 v71, vcc, 0, v67, vcc
	v_lshl_add_u64 v[122:123], v[66:67], 0, s[2:3]
	v_add_co_u32_e32 v66, vcc, 0xb0000, v66
	global_load_dwordx4 v[94:97], v[128:129], off
	global_load_dwordx4 v[90:93], v[128:129], off offset:256
	v_addc_co_u32_e32 v67, vcc, 0, v67, vcc
	global_load_dwordx4 v[82:85], v[126:127], off offset:256
	global_load_dwordx4 v[74:77], v[124:125], off offset:256
	global_load_dwordx4 v[78:81], v[70:71], off
	s_nop 0
	global_load_dwordx4 v[70:73], v[66:67], off
	global_load_dwordx4 v[86:89], v[68:69], off
	s_nop 0
	global_load_dwordx4 v[66:69], v[122:123], off offset:256
	s_add_i32 s2, s11, 0xffff0080
	s_lshr_b32 s2, s2, 5
	s_add_i32 s2, s2, 32
	v_ashrrev_i32_e32 v132, 11, v98
	v_mov_b32_e32 v98, s2
	s_mov_b32 s2, 0xff80
	v_cmp_gt_i32_e32 vcc, s2, v214
	v_readlane_b32 s2, v254, 59
	v_readlane_b32 s3, v254, 60
	v_cndmask_b32_e32 v100, v98, v132, vcc
	v_mov_b64_e32 v[106:107], v[118:119]
	v_mov_b64_e32 v[98:99], s[2:3]
	s_movk_i32 s2, 0x6000
	v_mad_i64_i32 v[98:99], s[2:3], v100, s2, v[98:99]
	v_lshl_add_u64 v[130:131], v[212:213], 2, v[98:99]
	s_and_b64 vcc, exec, s[0:1]
	v_mov_b64_e32 v[108:109], v[120:121]
	s_cbranch_vccnz .LBB0_679
	global_load_dwordx4 v[106:109], v[130:131], off

; __device__ __forceinline__ unsigned pk2(float lo, float hi) { const f32x2 v = {lo, hi}; const bf16v2_t b = __builtin_convertvector(v, bf16v2_t); return __builtin_bit_cast(unsigned, b); }
;     __device__ __forceinline__ void operator()(const f32x4 (&acc)[2][2][4][2], const pg8::Unit& u, int wr, int wc, int fr, int fq) const {
;     ...
;                 for (int ai = 0; ai < 2; ++ai) {
;                     u32x4 xv[4][2];
; #pragma unroll
;                     for (int m = 0; m < 4; ++m)
; #pragma unroll
;                         for (int bj = 0; bj < 2; ++bj) xv[m][bj] = *(const u32x4*)(X16 + (size_t)(row0 + ai * 128 + m * 16) * XS + c0 + bj * 128);
; #pragma unroll
;                     for (int m = 0; m < 4; ++m) {
;                         const int row = row0 + ai * 128 + m * 16;
;                         const float* gp = gate + (size_t)seq_of(row) * 6144 + c0;
; #pragma unroll
;                         for (int bj = 0; bj < 2; ++bj) {
;                             const f32x4 g0 = uni ? gU[bj][0] : *(const f32x4*)(gp + bj * 128), g1 = uni ? gU[bj][1] : *(const f32x4*)(gp + bj * 128 + 4);
;                             float x[8]; unpack8(xv[m][bj], x);
;                             const f32x4 a0 = acc[ai][bj][m][0], a1 = acc[ai][bj][m][1];
;                             u32x4 w; w.x = pk2(x[0] + g0[0] * a0[0], x[1] + g0[1] * a0[1]); w.y = pk2(x[2] + g0[2] * a0[2], x[3] + g0[3] * a0[3]);
;                             w.z = pk2(x[4] + g1[0] * a1[0], x[5] + g1[1] * a1[1]); w.w = pk2(x[6] + g1[2] * a1[2], x[7] + g1[3] * a1[3]);
;                             *(u32x4*)(X16 + (size_t)row * XS + c0 + bj * 128) = w;
;                         }
;                     }
;                     __builtin_amdgcn_sched_barrier(0);
.LBB0_683:
	v_mov_b64_e32 v[58:59], v[102:103]
	s_and_b64 vcc, exec, s[0:1]
	v_mov_b64_e32 v[60:61], v[104:105]
	s_cbranch_vccnz .LBB0_685
	global_load_dwordx4 v[58:61], v[130:131], off offset:528
	s_waitcnt vmcnt(0)
.LBB0_685:
	v_lshlrev_b32_e32 v94, 16, v90
	v_and_b32_e32 v95, 0xffff0000, v90
	v_pk_fma_f32 v[54:55], v[54:55], v[62:63], v[94:95]
	v_lshlrev_b32_e32 v62, 16, v91
	v_and_b32_e32 v63, 0xffff0000, v91
	v_pk_fma_f32 v[56:57], v[56:57], v[64:65], v[62:63]
	v_cvt_pk_bf16_f32 v54, v54, v55
	v_cvt_pk_bf16_f32 v55, v56, v57
	v_lshlrev_b32_e32 v56, 16, v92
	v_and_b32_e32 v57, 0xffff0000, v92
	v_pk_fma_f32 v[50:51], v[50:51], v[58:59], v[56:57]
	s_add_i32 s2, s11, 0xffff0090
	v_cvt_pk_bf16_f32 v56, v50, v51
	v_lshlrev_b32_e32 v50, 16, v93
	v_and_b32_e32 v51, 0xffff0000, v93
	s_lshr_b32 s2, s2, 5
	v_pk_fma_f32 v[50:51], v[52:53], v[60:61], v[50:51]
	s_add_i32 s2, s2, 32
	v_cvt_pk_bf16_f32 v57, v50, v51
	v_mov_b32_e32 v50, s2
	s_mov_b32 s2, 0xff70
	v_cmp_gt_i32_e32 vcc, s2, v214
	v_readlane_b32 s2, v254, 59
	v_readlane_b32 s3, v254, 60
	v_cndmask_b32_e32 v52, v50, v132, vcc
	global_store_dwordx4 v[128:129], v[54:57], off offset:256
	v_mov_b64_e32 v[50:51], s[2:3]
	s_movk_i32 s2, 0x6000
	v_mad_i64_i32 v[50:51], s[2:3], v52, s2, v[50:51]
	v_mov_b64_e32 v[54:55], v[118:119]
	v_lshl_add_u64 v[58:59], v[212:213], 2, v[50:51]
	s_and_b64 vcc, exec, s[0:1]
	v_mov_b64_e32 v[56:57], v[120:121]
	s_cbranch_vccnz .LBB0_687
	global_load_dwordx4 v[54:57], v[58:59], off
.LBB0_687:
	v_mov_b64_e32 v[50:51], v[114:115]
	s_and_b64 vcc, exec, s[0:1]
	v_mov_b64_e32 v[52:53], v[116:117]
	s_cbranch_vccnz .LBB0_689
	global_load_dwordx4 v[50:53], v[58:59], off offset:16
	s_waitcnt vmcnt(0)
.LBB0_689:
	v_lshlrev_b32_e32 v60, 16, v86
	v_and_b32_e32 v61, 0xffff0000, v86
	v_pk_fma_f32 v[46:47], v[46:47], v[54:55], v[60:61]
	v_lshlrev_b32_e32 v54, 16, v87
	v_and_b32_e32 v55, 0xffff0000, v87
	v_pk_fma_f32 v[48:49], v[48:49], v[56:57], v[54:55]
	v_cvt_pk_bf16_f32 v46, v46, v47
	v_cvt_pk_bf16_f32 v47, v48, v49
	v_lshlrev_b32_e32 v48, 16, v88
	v_and_b32_e32 v49, 0xffff0000, v88
	v_pk_fma_f32 v[42:43], v[42:43], v[50:51], v[48:49]
	s_and_b64 vcc, exec, s[0:1]
	v_cvt_pk_bf16_f32 v48, v42, v43
	v_lshlrev_b32_e32 v42, 16, v89
	v_and_b32_e32 v43, 0xffff0000, v89
	v_pk_fma_f32 v[42:43], v[44:45], v[52:53], v[42:43]
	s_nop 0
	v_cvt_pk_bf16_f32 v49, v42, v43
	global_store_dwordx4 v[126:127], v[46:49], off
	s_nop 1
	v_mov_b64_e32 v[46:47], v[110:111]
	v_mov_b64_e32 v[48:49], v[112:113]
	s_cbranch_vccnz .LBB0_691
	global_load_dwordx4 v[46:49], v[58:59], off offset:512
.LBB0_691:
	v_mov_b64_e32 v[42:43], v[102:103]
	s_and_b64 vcc, exec, s[0:1]
	v_mov_b64_e32 v[44:45], v[104:105]
	s_cbranch_vccnz .LBB0_693
	global_load_dwordx4 v[42:45], v[58:59], off offset:528
	s_waitcnt vmcnt(0)
.LBB0_693:
	v_lshlrev_b32_e32 v50, 16, v82
	v_and_b32_e32 v51, 0xffff0000, v82
	v_pk_fma_f32 v[38:39], v[38:39], v[46:47], v[50:51]
	v_lshlrev_b32_e32 v46, 16, v83
	v_and_b32_e32 v47, 0xffff0000, v83
	v_pk_fma_f32 v[40:41], v[40:41], v[48:49], v[46:47]
	v_cvt_pk_bf16_f32 v38, v38, v39
	v_cvt_pk_bf16_f32 v39, v40, v41
	v_lshlrev_b32_e32 v40, 16, v84
	v_and_b32_e32 v41, 0xffff0000, v84
	v_pk_fma_f32 v[34:35], v[34:35], v[42:43], v[40:41]
	s_add_i32 s2, s11, 0xffff00a0
	v_cvt_pk_bf16_f32 v40, v34, v35
	v_lshlrev_b32_e32 v34, 16, v85
	v_and_b32_e32 v35, 0xffff0000, v85
	s_lshr_b32 s2, s2, 5
	v_pk_fma_f32 v[34:35], v[36:37], v[44:45], v[34:35]
	s_add_i32 s2, s2, 32
	v_cvt_pk_bf16_f32 v41, v34, v35
	v_mov_b32_e32 v34, s2
	s_mov_b32 s2, 0xff60
	v_cmp_gt_i32_e32 vcc, s2, v214
	v_readlane_b32 s2, v254, 59
	v_readlane_b32 s3, v254, 60
	v_cndmask_b32_e32 v36, v34, v132, vcc
	global_store_dwordx4 v[126:127], v[38:41], off offset:256
	v_mov_b64_e32 v[34:35], s[2:3]
	s_movk_i32 s2, 0x6000
	v_mad_i64_i32 v[34:35], s[2:3], v36, s2, v[34:35]
	v_mov_b64_e32 v[38:39], v[118:119]
	v_lshl_add_u64 v[42:43], v[212:213], 2, v[34:35]
	s_and_b64 vcc, exec, s[0:1]
	v_mov_b64_e32 v[40:41], v[120:121]
	s_cbranch_vccnz .LBB0_695
	global_load_dwordx4 v[38:41], v[42:43], off
.LBB0_695:
	v_mov_b64_e32 v[34:35], v[114:115]
	s_and_b64 vcc, exec, s[0:1]
	v_mov_b64_e32 v[36:37], v[116:117]
	s_cbranch_vccnz .LBB0_697
	global_load_dwordx4 v[34:37], v[42:43], off offset:16
	s_waitcnt vmcnt(0)
; __device__ __forceinline__ unsigned pk2(float lo, float hi) { const f32x2 v = {lo, hi}; const bf16v2_t b = __builtin_convertvector(v, bf16v2_t); return __builtin_bit_cast(unsigned, b); }
;     __device__ __forceinline__ void operator()(const f32x4 (&acc)[2][2][4][2], const pg8::Unit& u, int wr, int wc, int fr, int fq) const {
;     ...
;                 for (int ai = 0; ai < 2; ++ai) {
;                     u32x4 xv[4][2];
; #pragma unroll
;                     for (int m = 0; m < 4; ++m)
; #pragma unroll
;                         for (int bj = 0; bj < 2; ++bj) xv[m][bj] = *(const u32x4*)(X16 + (size_t)(row0 + ai * 128 + m * 16) * XS + c0 + bj * 128);
; #pragma unroll
;                     for (int m = 0; m < 4; ++m) {
;                         const int row = row0 + ai * 128 + m * 16;
;                         const float* gp = gate + (size_t)seq_of(row) * 6144 + c0;
; #pragma unroll
;                         for (int bj = 0; bj < 2; ++bj) {
;                             const f32x4 g0 = uni ? gU[bj][0] : *(const f32x4*)(gp + bj * 128), g1 = uni ? gU[bj][1] : *(const f32x4*)(gp + bj * 128 + 4);
;                             float x[8]; unpack8(xv[m][bj], x);
;                             const f32x4 a0 = acc[ai][bj][m][0], a1 = acc[ai][bj][m][1];
;                             u32x4 w; w.x = pk2(x[0] + g0[0] * a0[0], x[1] + g0[1] * a0[1]); w.y = pk2(x[2] + g0[2] * a0[2], x[3] + g0[3] * a0[3]);
;                             w.z = pk2(x[4] + g1[0] * a1[0], x[5] + g1[1] * a1[1]); w.w = pk2(x[6] + g1[2] * a1[2], x[7] + g1[3] * a1[3]);
;                             *(u32x4*)(X16 + (size_t)row * XS + c0 + bj * 128) = w;
;                         }
;                     }
;                     __builtin_amdgcn_sched_barrier(0);
.LBB0_697:
	v_lshlrev_b32_e32 v44, 16, v78
	v_and_b32_e32 v45, 0xffff0000, v78
	v_pk_fma_f32 v[30:31], v[30:31], v[38:39], v[44:45]
	v_lshlrev_b32_e32 v38, 16, v79
	v_and_b32_e32 v39, 0xffff0000, v79
	v_pk_fma_f32 v[32:33], v[32:33], v[40:41], v[38:39]
	v_cvt_pk_bf16_f32 v30, v30, v31
	v_cvt_pk_bf16_f32 v31, v32, v33
	v_lshlrev_b32_e32 v32, 16, v80
	v_and_b32_e32 v33, 0xffff0000, v80
	v_pk_fma_f32 v[26:27], v[26:27], v[34:35], v[32:33]
	s_and_b64 vcc, exec, s[0:1]
	v_cvt_pk_bf16_f32 v32, v26, v27
	v_lshlrev_b32_e32 v26, 16, v81
	v_and_b32_e32 v27, 0xffff0000, v81
	v_pk_fma_f32 v[26:27], v[28:29], v[36:37], v[26:27]
	s_nop 0
	v_cvt_pk_bf16_f32 v33, v26, v27
	global_store_dwordx4 v[124:125], v[30:33], off
	s_nop 1
	v_mov_b64_e32 v[30:31], v[110:111]
	v_mov_b64_e32 v[32:33], v[112:113]
	s_cbranch_vccnz .LBB0_699
	global_load_dwordx4 v[30:33], v[42:43], off offset:512
.LBB0_699:
	v_mov_b64_e32 v[26:27], v[102:103]
	s_and_b64 vcc, exec, s[0:1]
	v_mov_b64_e32 v[28:29], v[104:105]
	s_cbranch_vccnz .LBB0_701
	global_load_dwordx4 v[26:29], v[42:43], off offset:528
	s_waitcnt vmcnt(0)
.LBB0_701:
	v_lshlrev_b32_e32 v34, 16, v74
	v_and_b32_e32 v35, 0xffff0000, v74
	v_pk_fma_f32 v[22:23], v[22:23], v[30:31], v[34:35]
	v_lshlrev_b32_e32 v30, 16, v75
	v_and_b32_e32 v31, 0xffff0000, v75
	v_pk_fma_f32 v[24:25], v[24:25], v[32:33], v[30:31]
	v_cvt_pk_bf16_f32 v22, v22, v23
	v_cvt_pk_bf16_f32 v23, v24, v25
	v_lshlrev_b32_e32 v24, 16, v76
	v_and_b32_e32 v25, 0xffff0000, v76
	v_pk_fma_f32 v[18:19], v[18:19], v[26:27], v[24:25]
	s_add_i32 s11, s11, 0xffff00b0
	v_cvt_pk_bf16_f32 v24, v18, v19
	v_lshlrev_b32_e32 v18, 16, v77
	v_and_b32_e32 v19, 0xffff0000, v77
	s_lshr_b32 s2, s11, 5
	v_pk_fma_f32 v[18:19], v[20:21], v[28:29], v[18:19]
	s_add_i32 s2, s2, 32
	v_cvt_pk_bf16_f32 v25, v18, v19
	v_mov_b32_e32 v18, s2
	s_mov_b32 s2, 0xff50
	v_cmp_gt_i32_e32 vcc, s2, v214
	v_readlane_b32 s2, v254, 59
	v_readlane_b32 s3, v254, 60
	v_cndmask_b32_e32 v20, v18, v132, vcc
	s_and_b64 vcc, exec, s[0:1]
	v_mov_b64_e32 v[18:19], s[2:3]
	s_movk_i32 s2, 0x6000
	v_mad_i64_i32 v[18:19], s[2:3], v20, s2, v[18:19]
	v_lshl_add_u64 v[18:19], v[212:213], 2, v[18:19]
	global_store_dwordx4 v[124:125], v[22:25], off offset:256
	s_cbranch_vccnz .LBB0_703
	global_load_dwordx4 v[118:121], v[18:19], off
.LBB0_703:
	s_and_b64 vcc, exec, s[0:1]
	s_cbranch_vccnz .LBB0_705
	global_load_dwordx4 v[114:117], v[18:19], off offset:16
	s_waitcnt vmcnt(0)
.LBB0_705:
	v_lshlrev_b32_e32 v20, 16, v70
	v_and_b32_e32 v21, 0xffff0000, v70
	v_pk_fma_f32 v[14:15], v[14:15], v[118:119], v[20:21]
	v_lshlrev_b32_e32 v20, 16, v71
	v_and_b32_e32 v21, 0xffff0000, v71
	v_pk_fma_f32 v[16:17], v[16:17], v[120:121], v[20:21]
	v_cvt_pk_bf16_f32 v14, v14, v15
	v_cvt_pk_bf16_f32 v15, v16, v17
	v_lshlrev_b32_e32 v16, 16, v72
	v_and_b32_e32 v17, 0xffff0000, v72
	v_pk_fma_f32 v[10:11], v[10:11], v[114:115], v[16:17]
	s_and_b64 vcc, exec, s[0:1]
	v_cvt_pk_bf16_f32 v16, v10, v11
	v_lshlrev_b32_e32 v10, 16, v73
	v_and_b32_e32 v11, 0xffff0000, v73
	v_pk_fma_f32 v[10:11], v[12:13], v[116:117], v[10:11]
	s_nop 0
	v_cvt_pk_bf16_f32 v17, v10, v11
	global_store_dwordx4 v[122:123], v[14:17], off
	s_cbranch_vccnz .LBB0_707
	global_load_dwordx4 v[110:113], v[18:19], off offset:512
.LBB0_707:
	s_and_b64 vcc, exec, s[0:1]
	s_cbranch_vccnz .LBB0_709
	global_load_dwordx4 v[102:105], v[18:19], off offset:528
	s_waitcnt vmcnt(0)
.LBB0_709:
	v_lshlrev_b32_e32 v10, 16, v66
	v_and_b32_e32 v11, 0xffff0000, v66
	v_pk_fma_f32 v[6:7], v[6:7], v[110:111], v[10:11]
	v_lshlrev_b32_e32 v10, 16, v67
	v_and_b32_e32 v11, 0xffff0000, v67
	v_pk_fma_f32 v[8:9], v[8:9], v[112:113], v[10:11]
	v_cvt_pk_bf16_f32 v6, v6, v7
	v_cvt_pk_bf16_f32 v7, v8, v9
	v_lshlrev_b32_e32 v8, 16, v68
	v_and_b32_e32 v9, 0xffff0000, v68
	v_pk_fma_f32 v[2:3], v[2:3], v[102:103], v[8:9]
	s_nop 0
	v_cvt_pk_bf16_f32 v8, v2, v3
	v_lshlrev_b32_e32 v2, 16, v69
	v_and_b32_e32 v3, 0xffff0000, v69
	v_pk_fma_f32 v[2:3], v[4:5], v[104:105], v[2:3]
	s_nop 0
	v_cvt_pk_bf16_f32 v9, v2, v3
	global_store_dwordx4 v[122:123], v[6:9], off offset:256
	s_andn2_b64 vcc, exec, s[36:37]
	s_mov_b64 s[0:1], -1
	s_cbranch_vccnz .LBB0_568
	s_branch .LBB0_712

; __device__ __forceinline__ void gdn_pre_phase(const Args& a, LAS unsigned char* lds, int slot) {
;     ...
;             const int base = quad * 16, cc = r;
;             for (int i = 1; i < 16; ++i) {
;                 float tacc = 0.f;
;                 for (int j = 0; j < i; ++j) {
;                     const float aij = AT[(base + i) * 65 + base + j];
;                     const float tj = (j > cc) ? AT[(base + j) * 65 + base + cc] : (j == cc ? 1.f : 0.f);
;                     tacc -= aij * tj;
;                 }
;                 asm volatile("s_waitcnt lgkmcnt(0)" ::: "memory");
;                 if (cc < i) AT[(base + i) * 65 + base + cc] = tacc;
;                 asm volatile("s_waitcnt lgkmcnt(0)" ::: "memory");
;             }
; #pragma unroll 1
;             for (int lev = 1; lev < 4; ++lev)
; #pragma unroll 1
;                 for (int bb = 0; bb < 4 - lev; ++bb) {
;                     const int aa = bb + lev, q4 = quad * 4;
;                     float mv[4] = {0.f, 0.f, 0.f, 0.f};
;                     for (int cb = bb; cb < aa; ++cb) {
;                         for (int k = 0; k < 16; ++k) {
;                             float tk;
;                             if (cb == bb) tk = (cc < k) ? AT[(bb * 16 + k) * 65 + bb * 16 + cc] : (cc == k ? 1.f : 0.f);
;                             else tk = AT[(bb * 16 + k) * 65 + cb * 16 + cc];
; #pragma unroll
;                             for (int jj = 0; jj < 4; ++jj) mv[jj] += AT[(aa * 16 + q4 + jj) * 65 + cb * 16 + k] * tk;
;                         }
;                     }
;                     asm volatile("s_waitcnt lgkmcnt(0)" ::: "memory");
; #pragma unroll
;                     for (int jj = 0; jj < 4; ++jj) AT[(bb * 16 + q4 + jj) * 65 + aa * 16 + cc] = mv[jj];
;                     asm volatile("s_waitcnt lgkmcnt(0)" ::: "memory");
;                     float tv[4] = {mv[0], mv[1], mv[2], mv[3]};
;                     for (int k = 0; k < 16; ++k) {
;                         const float mk = AT[(bb * 16 + k) * 65 + aa * 16 + cc];
; #pragma unroll
;                         for (int jj = 0; jj < 4; ++jj) { const int ii = q4 + jj; const float dv = AT[(aa * 16 + ii) * 65 + aa * 16 + k]; if (k < ii) tv[jj] += dv * mk; }
;                     }
;                     asm volatile("s_waitcnt lgkmcnt(0)" ::: "memory");
; #pragma unroll
.LBB0_2071:
	s_or_b64 exec, exec, s[0:1]
	v_cmp_eq_u32_e32 vcc, 1, v0
	v_readlane_b32 s38, v255, 13
	v_readlane_b32 s39, v255, 14
	v_cndmask_b32_e64 v63, 0, 1.0, vcc
	v_cmp_eq_u32_e32 vcc, 2, v0
	s_waitcnt lgkmcnt(13)
	v_lshlrev_b32_e32 v2, 2, v0
	v_ashrrev_i32_e32 v3, 2, v4
	v_cndmask_b32_e64 v69, 0, 1.0, vcc
	v_cmp_eq_u32_e32 vcc, 3, v0
	s_waitcnt lgkmcnt(9)
	v_cndmask_b32_e64 v18, 0, 1.0, s[38:39]
	v_readlane_b32 s38, v255, 3
	v_cndmask_b32_e64 v75, 0, 1.0, vcc
	v_cmp_eq_u32_e32 vcc, 4, v0
	s_waitcnt lgkmcnt(0)
	v_and_b32_e32 v39, -4, v3
	v_add_u32_e32 v105, s38, v2
	v_cndmask_b32_e64 v81, 0, 1.0, vcc
	v_cmp_eq_u32_e32 vcc, 5, v0
	s_movk_i32 s38, 0x410
	v_or_b32_e32 v51, 2, v39
	v_cndmask_b32_e64 v87, 0, 1.0, vcc
	v_cmp_eq_u32_e32 vcc, 6, v0
	v_or_b32_e32 v57, 3, v3
	s_waitcnt lgkmcnt(1)
	v_add_u32_e32 v33, s49, v2
	v_cndmask_b32_e64 v96, 0, 1.0, vcc
	v_cmp_eq_u32_e32 vcc, 7, v0
	s_mov_b32 s33, 3
	v_cmp_lt_i32_e64 s[66:67], 3, v3
	v_cndmask_b32_e64 v97, 0, 1.0, vcc
	v_cmp_eq_u32_e32 vcc, 8, v0
	s_mov_b32 s42, 1
	v_or_b32_e32 v45, 1, v39
	v_cndmask_b32_e64 v98, 0, 1.0, vcc
	v_cmp_eq_u32_e32 vcc, 9, v0
	v_cmp_lt_i32_e64 s[68:69], -1, v3
	v_cmp_lt_i32_e64 s[70:71], 3, v51
	v_cndmask_b32_e64 v99, 0, 1.0, vcc
	v_cmp_eq_u32_e32 vcc, 10, v0
	v_cmp_lt_i32_e64 s[72:73], 3, v57
	v_cmp_lt_i32_e64 s[74:75], 4, v39
	v_cndmask_b32_e64 v100, 0, 1.0, vcc
	v_cmp_eq_u32_e32 vcc, 11, v0
	v_cmp_lt_i32_e64 s[76:77], 4, v57
	v_cmp_lt_i32_e64 s[78:79], 5, v39
	v_cndmask_b32_e64 v101, 0, 1.0, vcc
	v_cmp_eq_u32_e32 vcc, 12, v0
	v_cmp_lt_i32_e64 s[80:81], 5, v51
	v_cmp_lt_i32_e64 s[82:83], 5, v57
	v_cndmask_b32_e64 v102, 0, 1.0, vcc
	v_cmp_eq_u32_e32 vcc, 13, v0
	v_cmp_lt_i32_e64 s[84:85], 6, v39
	v_cmp_lt_i32_e64 s[86:87], 6, v57
	v_cndmask_b32_e64 v103, 0, 1.0, vcc
	v_cmp_eq_u32_e32 vcc, 14, v0
	v_lshrrev_b32_e32 v0, 2, v3
	v_mul_lo_u32 v0, v0, s38
	v_readlane_b32 s38, v255, 4
	v_cmp_lt_i32_e64 s[88:89], 7, v39
	v_cmp_lt_i32_e64 s[90:91], 7, v51
	v_cmp_lt_i32_e64 s[92:93], 7, v57
	v_cmp_lt_i32_e64 s[94:95], 8, v39
	v_cmp_lt_i32_e64 s[96:97], 8, v57
	v_cmp_lt_i32_e64 s[2:3], 9, v39
	v_cmp_lt_i32_e64 s[4:5], 9, v51
	v_cmp_lt_i32_e64 s[6:7], 9, v57
	v_cmp_lt_i32_e64 s[8:9], 10, v39
	v_cmp_lt_i32_e64 s[10:11], 10, v57
	v_cmp_lt_i32_e64 s[12:13], 11, v39
	v_cmp_lt_i32_e64 s[14:15], 11, v51
	v_cmp_lt_i32_e64 s[16:17], 11, v57
	v_cmp_lt_i32_e64 s[18:19], 12, v39
	v_cmp_lt_i32_e64 s[20:21], 12, v57
	v_cmp_lt_i32_e64 s[22:23], 13, v39
	v_cmp_lt_i32_e64 s[24:25], 13, v51
	v_cmp_lt_i32_e64 s[26:27], 13, v57
	v_cmp_lt_i32_e64 s[28:29], 14, v39
	v_cmp_lt_i32_e64 s[30:31], 14, v57
	v_cmp_lt_i32_e64 s[34:35], 15, v39
	v_cmp_lt_i32_e64 s[0:1], 15, v51
	v_cmp_lt_i32_e64 s[36:37], 15, v57
	v_cndmask_b32_e64 v104, 0, 1.0, vcc
	v_mov_b32_e32 v19, v18
	v_add_u32_e32 v106, s38, v0
	s_mov_b64 exec, -1
	v_and_b32_e32 v0, 15, v174
	v_lshrrev_b32_e32 v9, 4, v174
	v_mul_u32_u24_e32 v2, 0x41, v0
	v_mul_u32_u24_e32 v3, 0x41, v9
	v_mul_u32_u24_e32 v4, 0x104, v9
	v_add_u32_e32 v2, v2, v9
	v_add_u32_e32 v3, v3, v0
	v_add_u32_e32 v4, v4, v0
	v_lshl_add_u32 v2, v2, 2, s49
	v_lshl_add_u32 v3, v3, 2, s49
	v_lshl_add_u32 v4, v4, 2, s49
	v_sub_u32_e32 v0, v0, v9
	v_cmp_eq_u32_e32 vcc, 0, v0
	s_nop 1
	v_cndmask_b32_e64 v5, 0, 1.0, vcc
	v_cmp_eq_u32_e32 vcc, 4, v0
	s_nop 1
	v_cndmask_b32_e64 v6, 0, 1.0, vcc
	v_cmp_eq_u32_e32 vcc, 8, v0
	s_nop 1
	v_cndmask_b32_e64 v7, 0, 1.0, vcc
	v_cmp_eq_u32_e32 vcc, 12, v0
	s_nop 1
	v_cndmask_b32_e64 v8, 0, 1.0, vcc
	ds_read_b32 v10, v2 offset:4160
	ds_read_b32 v11, v2 offset:4176
	ds_read_b32 v12, v2 offset:4192
	ds_read_b32 v13, v2 offset:4208
	ds_read_b32 v14, v3 offset:0
	ds_read_b32 v15, v3 offset:1040
	ds_read_b32 v16, v3 offset:2080
	ds_read_b32 v17, v3 offset:3120
	ds_read_b32 v32, v2 offset:8384
	ds_read_b32 v34, v2 offset:8400
	ds_read_b32 v35, v2 offset:8416
	ds_read_b32 v36, v2 offset:8432
	ds_read_b32 v37, v3 offset:4224
	ds_read_b32 v38, v3 offset:5264
	ds_read_b32 v40, v3 offset:6304
	ds_read_b32 v41, v3 offset:7344
	ds_read_b32 v42, v2 offset:12608
	ds_read_b32 v43, v2 offset:12624
	ds_read_b32 v44, v2 offset:12640
	ds_read_b32 v46, v2 offset:12656
	ds_read_b32 v47, v3 offset:8448
	ds_read_b32 v48, v3 offset:9488
	ds_read_b32 v49, v3 offset:10528
	ds_read_b32 v50, v3 offset:11568
	s_waitcnt lgkmcnt(0)
	v_add_f32_e32 v14, v14, v5
	v_add_f32_e32 v15, v15, v6
	v_add_f32_e32 v16, v16, v7
	v_add_f32_e32 v17, v17, v8
	v_add_f32_e32 v37, v37, v5
	v_add_f32_e32 v38, v38, v6
	v_add_f32_e32 v40, v40, v7
	v_add_f32_e32 v41, v41, v8
	v_add_f32_e32 v47, v47, v5
	v_add_f32_e32 v48, v48, v6
	v_add_f32_e32 v49, v49, v7
	v_add_f32_e32 v50, v50, v8
	s_nop 1
	v_mfma_f32_16x16x4_f32 v[20:23], v10, v14, 0
	v_mfma_f32_16x16x4_f32 v[24:27], v32, v37, 0
	v_mfma_f32_16x16x4_f32 v[28:31], v42, v47, 0
	v_mfma_f32_16x16x4_f32 v[20:23], v11, v15, v[20:23]
	v_mfma_f32_16x16x4_f32 v[24:27], v34, v38, v[24:27]
	v_mfma_f32_16x16x4_f32 v[28:31], v43, v48, v[28:31]
	v_mfma_f32_16x16x4_f32 v[20:23], v12, v16, v[20:23]
	v_mfma_f32_16x16x4_f32 v[24:27], v35, v40, v[24:27]
	v_mfma_f32_16x16x4_f32 v[28:31], v44, v49, v[28:31]
	v_mfma_f32_16x16x4_f32 v[20:23], v13, v17, v[20:23]
	v_mfma_f32_16x16x4_f32 v[24:27], v36, v41, v[24:27]
	v_mfma_f32_16x16x4_f32 v[28:31], v46, v50, v[28:31]
	s_nop 9
	ds_write_b32 v4, v20 offset:64
	ds_write_b32 v4, v21 offset:324
	ds_write_b32 v4, v22 offset:584
	ds_write_b32 v4, v23 offset:844
	ds_write_b32 v4, v24 offset:4288
	ds_write_b32 v4, v25 offset:4548
	ds_write_b32 v4, v26 offset:4808
	ds_write_b32 v4, v27 offset:5068
	ds_write_b32 v4, v28 offset:8512
	ds_write_b32 v4, v29 offset:8772
	ds_write_b32 v4, v30 offset:9032
	ds_write_b32 v4, v31 offset:9292
	ds_read_b32 v10, v2 offset:4224
	ds_read_b32 v11, v2 offset:4240
	ds_read_b32 v12, v2 offset:4256
	ds_read_b32 v13, v2 offset:4272
	ds_read_b32 v14, v3 offset:64
	ds_read_b32 v15, v3 offset:1104
	ds_read_b32 v16, v3 offset:2144
	ds_read_b32 v17, v3 offset:3184
	ds_read_b32 v32, v2 offset:8448
	ds_read_b32 v34, v2 offset:8464
	ds_read_b32 v35, v2 offset:8480
	ds_read_b32 v36, v2 offset:8496
	ds_read_b32 v37, v3 offset:4288
	ds_read_b32 v38, v3 offset:5328
	ds_read_b32 v40, v3 offset:6368
	ds_read_b32 v41, v3 offset:7408
	ds_read_b32 v42, v2 offset:12672
	ds_read_b32 v43, v2 offset:12688
	ds_read_b32 v44, v2 offset:12704
	ds_read_b32 v46, v2 offset:12720
	ds_read_b32 v47, v3 offset:8512
	ds_read_b32 v48, v3 offset:9552
	ds_read_b32 v49, v3 offset:10592
	ds_read_b32 v50, v3 offset:11632
	s_waitcnt lgkmcnt(0)
; __device__ __forceinline__ void gdn_pre_phase(const Args& a, LAS unsigned char* lds, int slot) {
;     ...
;             for (int lev = 1; lev < 4; ++lev)
; #pragma unroll 1
;                 for (int bb = 0; bb < 4 - lev; ++bb) {
;                     const int aa = bb + lev, q4 = quad * 4;
;                     float mv[4] = {0.f, 0.f, 0.f, 0.f};
;                     for (int cb = bb; cb < aa; ++cb) {
;                         for (int k = 0; k < 16; ++k) {
;                             float tk;
;                             if (cb == bb) tk = (cc < k) ? AT[(bb * 16 + k) * 65 + bb * 16 + cc] : (cc == k ? 1.f : 0.f);
;                             else tk = AT[(bb * 16 + k) * 65 + cb * 16 + cc];
; #pragma unroll
;                             for (int jj = 0; jj < 4; ++jj) mv[jj] += AT[(aa * 16 + q4 + jj) * 65 + cb * 16 + k] * tk;
;                         }
;                     }
;                     asm volatile("s_waitcnt lgkmcnt(0)" ::: "memory");
; #pragma unroll
;                     for (int jj = 0; jj < 4; ++jj) AT[(bb * 16 + q4 + jj) * 65 + aa * 16 + cc] = mv[jj];
;                     asm volatile("s_waitcnt lgkmcnt(0)" ::: "memory");
;                     float tv[4] = {mv[0], mv[1], mv[2], mv[3]};
;                     for (int k = 0; k < 16; ++k) {
;                         const float mk = AT[(bb * 16 + k) * 65 + aa * 16 + cc];
; #pragma unroll
;                         for (int jj = 0; jj < 4; ++jj) { const int ii = q4 + jj; const float dv = AT[(aa * 16 + ii) * 65 + aa * 16 + k]; if (k < ii) tv[jj] += dv * mk; }
;                     }
;                     asm volatile("s_waitcnt lgkmcnt(0)" ::: "memory");
; #pragma unroll
;                     for (int jj = 0; jj < 4; ++jj) AT[(bb * 16 + q4 + jj) * 65 + aa * 16 + cc] = -tv[jj];
;                     asm volatile("s_waitcnt lgkmcnt(0)" ::: "memory");
;                 }
	v_mfma_f32_16x16x4_f32 v[20:23], v10, v14, v[20:23]
	v_mfma_f32_16x16x4_f32 v[24:27], v32, v37, v[24:27]
	v_mfma_f32_16x16x4_f32 v[28:31], v42, v47, v[28:31]
	v_mfma_f32_16x16x4_f32 v[20:23], v11, v15, v[20:23]
	v_mfma_f32_16x16x4_f32 v[24:27], v34, v38, v[24:27]
	v_mfma_f32_16x16x4_f32 v[28:31], v43, v48, v[28:31]
	v_mfma_f32_16x16x4_f32 v[20:23], v12, v16, v[20:23]
	v_mfma_f32_16x16x4_f32 v[24:27], v35, v40, v[24:27]
	v_mfma_f32_16x16x4_f32 v[28:31], v44, v49, v[28:31]
	v_mfma_f32_16x16x4_f32 v[20:23], v13, v17, v[20:23]
	v_mfma_f32_16x16x4_f32 v[24:27], v36, v41, v[24:27]
	v_mfma_f32_16x16x4_f32 v[28:31], v46, v50, v[28:31]
	s_nop 9
	v_xor_b32_e32 v20, 0x80000000, v20
	v_xor_b32_e32 v21, 0x80000000, v21
	v_xor_b32_e32 v22, 0x80000000, v22
	v_xor_b32_e32 v23, 0x80000000, v23
	v_xor_b32_e32 v24, 0x80000000, v24
	v_xor_b32_e32 v25, 0x80000000, v25
	v_xor_b32_e32 v26, 0x80000000, v26
	v_xor_b32_e32 v27, 0x80000000, v27
	v_xor_b32_e32 v28, 0x80000000, v28
	v_xor_b32_e32 v29, 0x80000000, v29
	v_xor_b32_e32 v30, 0x80000000, v30
	v_xor_b32_e32 v31, 0x80000000, v31
	ds_write_b32 v4, v20 offset:64
	ds_write_b32 v4, v21 offset:324
	ds_write_b32 v4, v22 offset:584
	ds_write_b32 v4, v23 offset:844
	ds_write_b32 v4, v24 offset:4288
	ds_write_b32 v4, v25 offset:4548
	ds_write_b32 v4, v26 offset:4808
	ds_write_b32 v4, v27 offset:5068
	ds_write_b32 v4, v28 offset:8512
	ds_write_b32 v4, v29 offset:8772
	ds_write_b32 v4, v30 offset:9032
	ds_write_b32 v4, v31 offset:9292
	ds_read_b32 v10, v2 offset:8320
	ds_read_b32 v11, v2 offset:8336
	ds_read_b32 v12, v2 offset:8352
	ds_read_b32 v13, v2 offset:8368
	ds_read_b32 v14, v3 offset:0
	ds_read_b32 v15, v3 offset:1040
	ds_read_b32 v16, v3 offset:2080
	ds_read_b32 v17, v3 offset:3120
	ds_read_b32 v32, v2 offset:8384
	ds_read_b32 v34, v2 offset:8400
	ds_read_b32 v35, v2 offset:8416
	ds_read_b32 v36, v2 offset:8432
	ds_read_b32 v37, v3 offset:64
	ds_read_b32 v38, v3 offset:1104
	ds_read_b32 v40, v3 offset:2144
	ds_read_b32 v41, v3 offset:3184
	ds_read_b32 v42, v2 offset:12544
	ds_read_b32 v43, v2 offset:12560
	ds_read_b32 v44, v2 offset:12576
	ds_read_b32 v46, v2 offset:12592
	ds_read_b32 v47, v3 offset:4224
	ds_read_b32 v48, v3 offset:5264
	ds_read_b32 v49, v3 offset:6304
	ds_read_b32 v50, v3 offset:7344
	ds_read_b32 v52, v2 offset:12608
	ds_read_b32 v53, v2 offset:12624
	ds_read_b32 v54, v2 offset:12640
	ds_read_b32 v55, v2 offset:12656
	ds_read_b32 v56, v3 offset:4288
	ds_read_b32 v58, v3 offset:5328
	ds_read_b32 v59, v3 offset:6368
	ds_read_b32 v60, v3 offset:7408
	s_waitcnt lgkmcnt(0)
	v_add_f32_e32 v14, v14, v5
	v_add_f32_e32 v15, v15, v6
	v_add_f32_e32 v16, v16, v7
	v_add_f32_e32 v17, v17, v8
	v_add_f32_e32 v47, v47, v5
	v_add_f32_e32 v48, v48, v6
	v_add_f32_e32 v49, v49, v7
	v_add_f32_e32 v50, v50, v8
	s_nop 1
	v_mfma_f32_16x16x4_f32 v[20:23], v10, v14, 0
	v_mfma_f32_16x16x4_f32 v[24:27], v42, v47, 0
	v_mfma_f32_16x16x4_f32 v[20:23], v11, v15, v[20:23]
	v_mfma_f32_16x16x4_f32 v[24:27], v43, v48, v[24:27]
	v_mfma_f32_16x16x4_f32 v[20:23], v12, v16, v[20:23]
	v_mfma_f32_16x16x4_f32 v[24:27], v44, v49, v[24:27]
	v_mfma_f32_16x16x4_f32 v[20:23], v13, v17, v[20:23]
	v_mfma_f32_16x16x4_f32 v[24:27], v46, v50, v[24:27]
	v_mfma_f32_16x16x4_f32 v[20:23], v32, v37, v[20:23]
	v_mfma_f32_16x16x4_f32 v[24:27], v52, v56, v[24:27]
	v_mfma_f32_16x16x4_f32 v[20:23], v34, v38, v[20:23]
	v_mfma_f32_16x16x4_f32 v[24:27], v53, v58, v[24:27]
	v_mfma_f32_16x16x4_f32 v[20:23], v35, v40, v[20:23]
	v_mfma_f32_16x16x4_f32 v[24:27], v54, v59, v[24:27]
	v_mfma_f32_16x16x4_f32 v[20:23], v36, v41, v[20:23]
	v_mfma_f32_16x16x4_f32 v[24:27], v55, v60, v[24:27]
	s_nop 9
	ds_write_b32 v4, v20 offset:128
	ds_write_b32 v4, v21 offset:388
	ds_write_b32 v4, v22 offset:648
	ds_write_b32 v4, v23 offset:908
	ds_write_b32 v4, v24 offset:4352
	ds_write_b32 v4, v25 offset:4612
	ds_write_b32 v4, v26 offset:4872
	ds_write_b32 v4, v27 offset:5132
	ds_read_b32 v10, v2 offset:8448
	ds_read_b32 v11, v2 offset:8464
	ds_read_b32 v12, v2 offset:8480
	ds_read_b32 v13, v2 offset:8496
	ds_read_b32 v14, v3 offset:128
	ds_read_b32 v15, v3 offset:1168
	ds_read_b32 v16, v3 offset:2208
	ds_read_b32 v17, v3 offset:3248
	ds_read_b32 v32, v2 offset:12672
	ds_read_b32 v34, v2 offset:12688
	ds_read_b32 v35, v2 offset:12704
	ds_read_b32 v36, v2 offset:12720
	ds_read_b32 v37, v3 offset:4352
	ds_read_b32 v38, v3 offset:5392
	ds_read_b32 v40, v3 offset:6432
	ds_read_b32 v41, v3 offset:7472
	s_waitcnt lgkmcnt(0)
; __device__ __forceinline__ void gdn_pre_phase(const Args& a, LAS unsigned char* lds, int slot) {
;     ...
;             for (int lev = 1; lev < 4; ++lev)
; #pragma unroll 1
;                 for (int bb = 0; bb < 4 - lev; ++bb) {
;                     const int aa = bb + lev, q4 = quad * 4;
;                     float mv[4] = {0.f, 0.f, 0.f, 0.f};
;                     for (int cb = bb; cb < aa; ++cb) {
;                         for (int k = 0; k < 16; ++k) {
;                             float tk;
;                             if (cb == bb) tk = (cc < k) ? AT[(bb * 16 + k) * 65 + bb * 16 + cc] : (cc == k ? 1.f : 0.f);
;                             else tk = AT[(bb * 16 + k) * 65 + cb * 16 + cc];
; #pragma unroll
;                             for (int jj = 0; jj < 4; ++jj) mv[jj] += AT[(aa * 16 + q4 + jj) * 65 + cb * 16 + k] * tk;
;                         }
;                     }
;                     asm volatile("s_waitcnt lgkmcnt(0)" ::: "memory");
; #pragma unroll
;                     for (int jj = 0; jj < 4; ++jj) AT[(bb * 16 + q4 + jj) * 65 + aa * 16 + cc] = mv[jj];
;                     asm volatile("s_waitcnt lgkmcnt(0)" ::: "memory");
;                     float tv[4] = {mv[0], mv[1], mv[2], mv[3]};
;                     for (int k = 0; k < 16; ++k) {
;                         const float mk = AT[(bb * 16 + k) * 65 + aa * 16 + cc];
; #pragma unroll
;                         for (int jj = 0; jj < 4; ++jj) { const int ii = q4 + jj; const float dv = AT[(aa * 16 + ii) * 65 + aa * 16 + k]; if (k < ii) tv[jj] += dv * mk; }
;                     }
;                     asm volatile("s_waitcnt lgkmcnt(0)" ::: "memory");
; #pragma unroll
;                     for (int jj = 0; jj < 4; ++jj) AT[(bb * 16 + q4 + jj) * 65 + aa * 16 + cc] = -tv[jj];
;                     asm volatile("s_waitcnt lgkmcnt(0)" ::: "memory");
;                 }
	v_mfma_f32_16x16x4_f32 v[20:23], v10, v14, v[20:23]
	v_mfma_f32_16x16x4_f32 v[24:27], v32, v37, v[24:27]
	v_mfma_f32_16x16x4_f32 v[20:23], v11, v15, v[20:23]
	v_mfma_f32_16x16x4_f32 v[24:27], v34, v38, v[24:27]
	v_mfma_f32_16x16x4_f32 v[20:23], v12, v16, v[20:23]
	v_mfma_f32_16x16x4_f32 v[24:27], v35, v40, v[24:27]
	v_mfma_f32_16x16x4_f32 v[20:23], v13, v17, v[20:23]
	v_mfma_f32_16x16x4_f32 v[24:27], v36, v41, v[24:27]
	s_nop 9
	v_xor_b32_e32 v20, 0x80000000, v20
	v_xor_b32_e32 v21, 0x80000000, v21
	v_xor_b32_e32 v22, 0x80000000, v22
	v_xor_b32_e32 v23, 0x80000000, v23
	v_xor_b32_e32 v24, 0x80000000, v24
	v_xor_b32_e32 v25, 0x80000000, v25
	v_xor_b32_e32 v26, 0x80000000, v26
	v_xor_b32_e32 v27, 0x80000000, v27
	ds_write_b32 v4, v20 offset:128
	ds_write_b32 v4, v21 offset:388
	ds_write_b32 v4, v22 offset:648
	ds_write_b32 v4, v23 offset:908
	ds_write_b32 v4, v24 offset:4352
	ds_write_b32 v4, v25 offset:4612
	ds_write_b32 v4, v26 offset:4872
	ds_write_b32 v4, v27 offset:5132
	ds_read_b32 v10, v2 offset:12480
	ds_read_b32 v11, v2 offset:12496
	ds_read_b32 v12, v2 offset:12512
	ds_read_b32 v13, v2 offset:12528
	ds_read_b32 v14, v3 offset:0
	ds_read_b32 v15, v3 offset:1040
	ds_read_b32 v16, v3 offset:2080
	ds_read_b32 v17, v3 offset:3120
	ds_read_b32 v32, v2 offset:12544
	ds_read_b32 v34, v2 offset:12560
	ds_read_b32 v35, v2 offset:12576
	ds_read_b32 v36, v2 offset:12592
	ds_read_b32 v37, v3 offset:64
	ds_read_b32 v38, v3 offset:1104
	ds_read_b32 v40, v3 offset:2144
	ds_read_b32 v41, v3 offset:3184
	ds_read_b32 v42, v2 offset:12608
	ds_read_b32 v43, v2 offset:12624
	ds_read_b32 v44, v2 offset:12640
	ds_read_b32 v46, v2 offset:12656
	ds_read_b32 v47, v3 offset:128
	ds_read_b32 v48, v3 offset:1168
	ds_read_b32 v49, v3 offset:2208
	ds_read_b32 v50, v3 offset:3248
	s_waitcnt lgkmcnt(0)
	v_add_f32_e32 v14, v14, v5
	v_add_f32_e32 v15, v15, v6
	v_add_f32_e32 v16, v16, v7
	v_add_f32_e32 v17, v17, v8
	s_nop 1
	v_mfma_f32_16x16x4_f32 v[20:23], v10, v14, 0
	v_mfma_f32_16x16x4_f32 v[20:23], v11, v15, v[20:23]
	v_mfma_f32_16x16x4_f32 v[20:23], v12, v16, v[20:23]
	v_mfma_f32_16x16x4_f32 v[20:23], v13, v17, v[20:23]
	v_mfma_f32_16x16x4_f32 v[20:23], v32, v37, v[20:23]
	v_mfma_f32_16x16x4_f32 v[20:23], v34, v38, v[20:23]
	v_mfma_f32_16x16x4_f32 v[20:23], v35, v40, v[20:23]
	v_mfma_f32_16x16x4_f32 v[20:23], v36, v41, v[20:23]
	v_mfma_f32_16x16x4_f32 v[20:23], v42, v47, v[20:23]
	v_mfma_f32_16x16x4_f32 v[20:23], v43, v48, v[20:23]
	v_mfma_f32_16x16x4_f32 v[20:23], v44, v49, v[20:23]
	v_mfma_f32_16x16x4_f32 v[20:23], v46, v50, v[20:23]
	s_nop 9
	ds_write_b32 v4, v20 offset:192
	ds_write_b32 v4, v21 offset:452
	ds_write_b32 v4, v22 offset:712
	ds_write_b32 v4, v23 offset:972
	ds_read_b32 v10, v2 offset:12672
	ds_read_b32 v11, v2 offset:12688
	ds_read_b32 v12, v2 offset:12704
	ds_read_b32 v13, v2 offset:12720
	ds_read_b32 v14, v3 offset:192
	ds_read_b32 v15, v3 offset:1232
	ds_read_b32 v16, v3 offset:2272
	ds_read_b32 v17, v3 offset:3312
	s_waitcnt lgkmcnt(0)
	v_mfma_f32_16x16x4_f32 v[20:23], v10, v14, v[20:23]
	v_mfma_f32_16x16x4_f32 v[20:23], v11, v15, v[20:23]
	v_mfma_f32_16x16x4_f32 v[20:23], v12, v16, v[20:23]
	v_mfma_f32_16x16x4_f32 v[20:23], v13, v17, v[20:23]
	s_nop 9
	v_xor_b32_e32 v20, 0x80000000, v20
	v_xor_b32_e32 v21, 0x80000000, v21
	v_xor_b32_e32 v22, 0x80000000, v22
	v_xor_b32_e32 v23, 0x80000000, v23
	ds_write_b32 v4, v20 offset:192
	ds_write_b32 v4, v21 offset:452
	ds_write_b32 v4, v22 offset:712
	ds_write_b32 v4, v23 offset:972
	s_waitcnt lgkmcnt(0)

; __device__ __forceinline__ unsigned pk2(float lo, float hi) { const f32x2 v = {lo, hi}; const bf16v2_t b = __builtin_convertvector(v, bf16v2_t); return __builtin_bit_cast(unsigned, b); }
;     __device__ __forceinline__ void operator()(const f32x4 (&acc)[2][2][4][2], const pg8::Unit& u, int wr, int wc, int fr, int fq) const {
;     ...
; #pragma unroll
;                 for (int ai = 0; ai < 2; ++ai) {
;                     u32x4 xv[4][2];
; #pragma unroll
;                     for (int m = 0; m < 4; ++m)
; #pragma unroll
;                         for (int bj = 0; bj < 2; ++bj) xv[m][bj] = *(const u32x4*)(X16 + (size_t)(row0 + ai * 128 + m * 16) * XS + c0 + bj * 128);
; #pragma unroll
;                     for (int m = 0; m < 4; ++m) {
;                         const int row = row0 + ai * 128 + m * 16;
;                         const float* gp = gate + (size_t)seq_of(row) * 6144 + c0;
; #pragma unroll
;                         for (int bj = 0; bj < 2; ++bj) {
;                             const f32x4 g0 = uni ? gU[bj][0] : *(const f32x4*)(gp + bj * 128), g1 = uni ? gU[bj][1] : *(const f32x4*)(gp + bj * 128 + 4);
;                             float x[8]; unpack8(xv[m][bj], x);
;                             const f32x4 a0 = acc[ai][bj][m][0], a1 = acc[ai][bj][m][1];
;                             u32x4 w; w.x = pk2(x[0] + g0[0] * a0[0], x[1] + g0[1] * a0[1]); w.y = pk2(x[2] + g0[2] * a0[2], x[3] + g0[3] * a0[3]);
;                             w.z = pk2(x[4] + g1[0] * a1[0], x[5] + g1[1] * a1[1]); w.w = pk2(x[6] + g1[2] * a1[2], x[7] + g1[3] * a1[3]);
;                             *(u32x4*)(X16 + (size_t)row * XS + c0 + bj * 128) = w;
;                         }
;                     }
;                     __builtin_amdgcn_sched_barrier(0);
;                 }
.LBB0_3086:
	v_mov_b64_e32 v[180:181], v[116:117]
	s_and_b64 vcc, exec, s[2:3]
	v_mov_b64_e32 v[178:179], v[114:115]
	s_cbranch_vccnz .LBB0_3088
	global_load_dwordx4 v[178:181], v[232:233], off offset:16
	s_waitcnt vmcnt(0)
.LBB0_3088:
	v_lshlrev_b32_e32 v246, 16, v174
	v_and_b32_e32 v247, 0xffff0000, v174
	v_lshlrev_b32_e32 v174, 16, v175
	v_and_b32_e32 v175, 0xffff0000, v175
	v_pk_fma_f32 v[142:143], v[142:143], v[182:183], v[246:247]
	v_pk_fma_f32 v[144:145], v[144:145], v[184:185], v[174:175]
	v_cvt_pk_bf16_f32 v142, v142, v143
	v_cvt_pk_bf16_f32 v143, v144, v145
	v_lshlrev_b32_e32 v144, 16, v176
	v_and_b32_e32 v145, 0xffff0000, v176
	v_pk_fma_f32 v[138:139], v[138:139], v[178:179], v[144:145]
	s_and_b64 vcc, exec, s[2:3]
	v_cvt_pk_bf16_f32 v144, v138, v139
	v_lshlrev_b32_e32 v138, 16, v177
	v_and_b32_e32 v139, 0xffff0000, v177
	v_pk_fma_f32 v[138:139], v[140:141], v[180:181], v[138:139]
	s_nop 0
	v_cvt_pk_bf16_f32 v145, v138, v139
	global_store_dwordx4 v[230:231], v[142:145], off
	s_nop 1
	v_mov_b64_e32 v[144:145], v[112:113]
	v_mov_b64_e32 v[142:143], v[110:111]
	s_cbranch_vccnz .LBB0_3090
	global_load_dwordx4 v[142:145], v[232:233], off offset:512
.LBB0_3090:
	v_mov_b64_e32 v[140:141], v[104:105]
	s_and_b64 vcc, exec, s[2:3]
	v_mov_b64_e32 v[138:139], v[102:103]
	s_cbranch_vccnz .LBB0_3092
	global_load_dwordx4 v[138:141], v[232:233], off offset:528
	s_waitcnt vmcnt(0)
.LBB0_3092:
	v_lshlrev_b32_e32 v174, 16, v170
	v_and_b32_e32 v175, 0xffff0000, v170
	v_pk_fma_f32 v[134:135], v[134:135], v[142:143], v[174:175]
	v_lshlrev_b32_e32 v142, 16, v171
	v_and_b32_e32 v143, 0xffff0000, v171
	v_pk_fma_f32 v[136:137], v[136:137], v[144:145], v[142:143]
	v_cvt_pk_bf16_f32 v134, v134, v135
	v_cvt_pk_bf16_f32 v135, v136, v137
	v_lshlrev_b32_e32 v136, 16, v172
	v_and_b32_e32 v137, 0xffff0000, v172
	v_pk_fma_f32 v[130:131], v[130:131], v[138:139], v[136:137]
	s_add_i32 s14, s16, 0xffff0010
	v_cvt_pk_bf16_f32 v136, v130, v131
	v_lshlrev_b32_e32 v130, 16, v173
	v_and_b32_e32 v131, 0xffff0000, v173
	s_lshr_b32 s14, s14, 5
	v_pk_fma_f32 v[130:131], v[132:133], v[140:141], v[130:131]
	s_add_i32 s14, s14, 32
	v_cvt_pk_bf16_f32 v137, v130, v131
	v_mov_b32_e32 v130, s14
	v_mov_b32_e32 v131, s17
	v_cmp_gt_i32_e32 vcc, s57, v228
	s_movk_i32 s14, 0x6000
	global_store_dwordx4 v[230:231], v[134:137], off offset:256
	v_cndmask_b32_e32 v132, v130, v131, vcc
	v_mov_b64_e32 v[130:131], s[6:7]
	v_mad_i64_i32 v[130:131], s[14:15], v132, s14, v[130:131]
	v_mov_b64_e32 v[136:137], v[120:121]
	v_lshl_add_u64 v[138:139], v[212:213], 2, v[130:131]
	s_and_b64 vcc, exec, s[2:3]
	v_mov_b64_e32 v[134:135], v[118:119]
	s_cbranch_vccnz .LBB0_3094
	global_load_dwordx4 v[134:137], v[138:139], off
.LBB0_3094:
	v_mov_b64_e32 v[132:133], v[116:117]
	s_and_b64 vcc, exec, s[2:3]
	v_mov_b64_e32 v[130:131], v[114:115]
	s_cbranch_vccnz .LBB0_3096
	global_load_dwordx4 v[130:133], v[138:139], off offset:16
	s_waitcnt vmcnt(0)
.LBB0_3096:
	v_lshlrev_b32_e32 v140, 16, v166
	v_and_b32_e32 v141, 0xffff0000, v166
	v_pk_fma_f32 v[126:127], v[126:127], v[134:135], v[140:141]
	v_lshlrev_b32_e32 v134, 16, v167
	v_and_b32_e32 v135, 0xffff0000, v167
	v_pk_fma_f32 v[128:129], v[128:129], v[136:137], v[134:135]
	v_cvt_pk_bf16_f32 v126, v126, v127
	v_cvt_pk_bf16_f32 v127, v128, v129
	v_lshlrev_b32_e32 v128, 16, v168
	v_and_b32_e32 v129, 0xffff0000, v168
	v_pk_fma_f32 v[122:123], v[122:123], v[130:131], v[128:129]
	s_and_b64 vcc, exec, s[2:3]
	v_cvt_pk_bf16_f32 v128, v122, v123
	v_lshlrev_b32_e32 v122, 16, v169
	v_and_b32_e32 v123, 0xffff0000, v169
	v_pk_fma_f32 v[122:123], v[124:125], v[132:133], v[122:123]
	s_nop 0
	v_cvt_pk_bf16_f32 v129, v122, v123
	global_store_dwordx4 v[226:227], v[126:129], off
	s_nop 1
	v_mov_b64_e32 v[128:129], v[112:113]
	v_mov_b64_e32 v[126:127], v[110:111]
	s_cbranch_vccnz .LBB0_3098
	global_load_dwordx4 v[126:129], v[138:139], off offset:512
.LBB0_3098:
	v_mov_b64_e32 v[124:125], v[104:105]
	s_and_b64 vcc, exec, s[2:3]
	v_mov_b64_e32 v[122:123], v[102:103]
	s_cbranch_vccnz .LBB0_3100
	global_load_dwordx4 v[122:125], v[138:139], off offset:528
	s_waitcnt vmcnt(0)
.LBB0_3100:
	v_lshlrev_b32_e32 v130, 16, v162
	v_and_b32_e32 v131, 0xffff0000, v162
	v_pk_fma_f32 v[106:107], v[106:107], v[126:127], v[130:131]
	v_lshlrev_b32_e32 v126, 16, v163
	v_and_b32_e32 v127, 0xffff0000, v163
	v_pk_fma_f32 v[108:109], v[108:109], v[128:129], v[126:127]
	v_cvt_pk_bf16_f32 v106, v106, v107
	v_cvt_pk_bf16_f32 v107, v108, v109
	v_lshlrev_b32_e32 v108, 16, v164
	v_and_b32_e32 v109, 0xffff0000, v164
	v_pk_fma_f32 v[98:99], v[98:99], v[122:123], v[108:109]
	s_add_i32 s14, s16, 0xffff0020
	v_cvt_pk_bf16_f32 v108, v98, v99
	v_lshlrev_b32_e32 v98, 16, v165
	v_and_b32_e32 v99, 0xffff0000, v165
	s_lshr_b32 s14, s14, 5
	v_pk_fma_f32 v[98:99], v[100:101], v[124:125], v[98:99]
	s_add_i32 s14, s14, 32
	v_cvt_pk_bf16_f32 v109, v98, v99
	v_mov_b32_e32 v98, s14
	v_mov_b32_e32 v99, s17
	v_cmp_gt_i32_e32 vcc, s57, v224
	s_movk_i32 s14, 0x6000
	global_store_dwordx4 v[226:227], v[106:109], off offset:256
	v_cndmask_b32_e32 v100, v98, v99, vcc
	v_mov_b64_e32 v[98:99], s[6:7]
	v_mad_i64_i32 v[98:99], s[14:15], v100, s14, v[98:99]
	v_mov_b64_e32 v[106:107], v[118:119]
	v_lshl_add_u64 v[122:123], v[212:213], 2, v[98:99]
	s_and_b64 vcc, exec, s[2:3]
	v_mov_b64_e32 v[108:109], v[120:121]
	s_cbranch_vccnz .LBB0_3102
	global_load_dwordx4 v[106:109], v[122:123], off
.LBB0_3102:
	v_mov_b64_e32 v[98:99], v[114:115]
	s_and_b64 vcc, exec, s[2:3]
	v_mov_b64_e32 v[100:101], v[116:117]
	s_cbranch_vccnz .LBB0_3104
	global_load_dwordx4 v[98:101], v[122:123], off offset:16
	s_waitcnt vmcnt(0)
; __device__ __forceinline__ unsigned pk2(float lo, float hi) { const f32x2 v = {lo, hi}; const bf16v2_t b = __builtin_convertvector(v, bf16v2_t); return __builtin_bit_cast(unsigned, b); }
;     __device__ __forceinline__ void operator()(const f32x4 (&acc)[2][2][4][2], const pg8::Unit& u, int wr, int wc, int fr, int fq) const {
;     ...
; #pragma unroll
;                 for (int ai = 0; ai < 2; ++ai) {
;                     u32x4 xv[4][2];
; #pragma unroll
;                     for (int m = 0; m < 4; ++m)
; #pragma unroll
;                         for (int bj = 0; bj < 2; ++bj) xv[m][bj] = *(const u32x4*)(X16 + (size_t)(row0 + ai * 128 + m * 16) * XS + c0 + bj * 128);
; #pragma unroll
;                     for (int m = 0; m < 4; ++m) {
;                         const int row = row0 + ai * 128 + m * 16;
;                         const float* gp = gate + (size_t)seq_of(row) * 6144 + c0;
; #pragma unroll
;                         for (int bj = 0; bj < 2; ++bj) {
;                             const f32x4 g0 = uni ? gU[bj][0] : *(const f32x4*)(gp + bj * 128), g1 = uni ? gU[bj][1] : *(const f32x4*)(gp + bj * 128 + 4);
;                             float x[8]; unpack8(xv[m][bj], x);
;                             const f32x4 a0 = acc[ai][bj][m][0], a1 = acc[ai][bj][m][1];
;                             u32x4 w; w.x = pk2(x[0] + g0[0] * a0[0], x[1] + g0[1] * a0[1]); w.y = pk2(x[2] + g0[2] * a0[2], x[3] + g0[3] * a0[3]);
;                             w.z = pk2(x[4] + g1[0] * a1[0], x[5] + g1[1] * a1[1]); w.w = pk2(x[6] + g1[2] * a1[2], x[7] + g1[3] * a1[3]);
;                             *(u32x4*)(X16 + (size_t)row * XS + c0 + bj * 128) = w;
;                         }
;                     }
;                     __builtin_amdgcn_sched_barrier(0);
;                 }
.LBB0_3104:
	v_lshlrev_b32_e32 v124, 16, v158
	v_and_b32_e32 v125, 0xffff0000, v158
	v_pk_fma_f32 v[94:95], v[94:95], v[106:107], v[124:125]
	v_lshlrev_b32_e32 v106, 16, v159
	v_and_b32_e32 v107, 0xffff0000, v159
	v_pk_fma_f32 v[96:97], v[96:97], v[108:109], v[106:107]
	v_cvt_pk_bf16_f32 v94, v94, v95
	v_cvt_pk_bf16_f32 v95, v96, v97
	v_lshlrev_b32_e32 v96, 16, v160
	v_and_b32_e32 v97, 0xffff0000, v160
	v_pk_fma_f32 v[90:91], v[90:91], v[98:99], v[96:97]
	s_and_b64 vcc, exec, s[2:3]
	v_cvt_pk_bf16_f32 v96, v90, v91
	v_lshlrev_b32_e32 v90, 16, v161
	v_and_b32_e32 v91, 0xffff0000, v161
	v_pk_fma_f32 v[90:91], v[92:93], v[100:101], v[90:91]
	s_nop 0
	v_cvt_pk_bf16_f32 v97, v90, v91
	global_store_dwordx4 v[222:223], v[94:97], off
	s_nop 1
	v_mov_b64_e32 v[94:95], v[110:111]
	v_mov_b64_e32 v[96:97], v[112:113]
	s_cbranch_vccnz .LBB0_3106
	global_load_dwordx4 v[94:97], v[122:123], off offset:512
.LBB0_3106:
	v_mov_b64_e32 v[90:91], v[102:103]
	s_and_b64 vcc, exec, s[2:3]
	v_mov_b64_e32 v[92:93], v[104:105]
	s_cbranch_vccnz .LBB0_3108
	global_load_dwordx4 v[90:93], v[122:123], off offset:528
	s_waitcnt vmcnt(0)
.LBB0_3108:
	v_lshlrev_b32_e32 v98, 16, v154
	v_and_b32_e32 v99, 0xffff0000, v154
	v_pk_fma_f32 v[86:87], v[86:87], v[94:95], v[98:99]
	v_lshlrev_b32_e32 v94, 16, v155
	v_and_b32_e32 v95, 0xffff0000, v155
	v_pk_fma_f32 v[88:89], v[88:89], v[96:97], v[94:95]
	v_cvt_pk_bf16_f32 v86, v86, v87
	v_cvt_pk_bf16_f32 v87, v88, v89
	v_lshlrev_b32_e32 v88, 16, v156
	v_and_b32_e32 v89, 0xffff0000, v156
	v_pk_fma_f32 v[82:83], v[82:83], v[90:91], v[88:89]
	s_add_i32 s14, s16, 0xffff0030
	v_cvt_pk_bf16_f32 v88, v82, v83
	v_lshlrev_b32_e32 v82, 16, v157
	v_and_b32_e32 v83, 0xffff0000, v157
	s_lshr_b32 s14, s14, 5
	v_pk_fma_f32 v[82:83], v[84:85], v[92:93], v[82:83]
	s_add_i32 s14, s14, 32
	v_cvt_pk_bf16_f32 v89, v82, v83
	v_mov_b32_e32 v82, s14
	v_mov_b32_e32 v83, s17
	v_cmp_gt_i32_e32 vcc, s57, v220
	s_movk_i32 s14, 0x6000
	global_store_dwordx4 v[222:223], v[86:89], off offset:256
	v_cndmask_b32_e32 v84, v82, v83, vcc
	v_mov_b64_e32 v[82:83], s[6:7]
	v_mad_i64_i32 v[82:83], s[14:15], v84, s14, v[82:83]
	v_mov_b64_e32 v[86:87], v[118:119]
	v_lshl_add_u64 v[90:91], v[212:213], 2, v[82:83]
	s_and_b64 vcc, exec, s[2:3]
	v_mov_b64_e32 v[88:89], v[120:121]
	s_cbranch_vccnz .LBB0_3110
	global_load_dwordx4 v[86:89], v[90:91], off
.LBB0_3110:
	v_mov_b64_e32 v[82:83], v[114:115]
	s_and_b64 vcc, exec, s[2:3]
	v_mov_b64_e32 v[84:85], v[116:117]
	s_cbranch_vccnz .LBB0_3112
	global_load_dwordx4 v[82:85], v[90:91], off offset:16
	s_waitcnt vmcnt(0)
.LBB0_3112:
	v_lshlrev_b32_e32 v92, 16, v150
	v_and_b32_e32 v93, 0xffff0000, v150
	v_pk_fma_f32 v[78:79], v[78:79], v[86:87], v[92:93]
	v_lshlrev_b32_e32 v86, 16, v151
	v_and_b32_e32 v87, 0xffff0000, v151
	v_pk_fma_f32 v[80:81], v[80:81], v[88:89], v[86:87]
	v_cvt_pk_bf16_f32 v78, v78, v79
	v_cvt_pk_bf16_f32 v79, v80, v81
	v_lshlrev_b32_e32 v80, 16, v152
	v_and_b32_e32 v81, 0xffff0000, v152
	v_pk_fma_f32 v[74:75], v[74:75], v[82:83], v[80:81]
	s_and_b64 vcc, exec, s[2:3]
	v_cvt_pk_bf16_f32 v80, v74, v75
	v_lshlrev_b32_e32 v74, 16, v153
	v_and_b32_e32 v75, 0xffff0000, v153
	v_pk_fma_f32 v[74:75], v[76:77], v[84:85], v[74:75]
	s_nop 0
	v_cvt_pk_bf16_f32 v81, v74, v75
	global_store_dwordx4 v[218:219], v[78:81], off
	s_nop 1
	v_mov_b64_e32 v[78:79], v[110:111]
	v_mov_b64_e32 v[80:81], v[112:113]
	s_cbranch_vccnz .LBB0_3114
	global_load_dwordx4 v[78:81], v[90:91], off offset:512
.LBB0_3114:
	v_mov_b64_e32 v[74:75], v[102:103]
	s_and_b64 vcc, exec, s[2:3]
	v_mov_b64_e32 v[76:77], v[104:105]
	s_cbranch_vccnz .LBB0_3116
	global_load_dwordx4 v[74:77], v[90:91], off offset:528
	s_waitcnt vmcnt(0)
.LBB0_3116:
	v_lshlrev_b32_e32 v82, 16, v146
	v_and_b32_e32 v83, 0xffff0000, v146
	v_pk_fma_f32 v[70:71], v[70:71], v[78:79], v[82:83]
	v_lshlrev_b32_e32 v78, 16, v147
	v_and_b32_e32 v79, 0xffff0000, v147
	v_pk_fma_f32 v[72:73], v[72:73], v[80:81], v[78:79]
	v_cvt_pk_bf16_f32 v70, v70, v71
	v_cvt_pk_bf16_f32 v71, v72, v73
	v_lshlrev_b32_e32 v72, 16, v148
	v_and_b32_e32 v73, 0xffff0000, v148
	v_pk_fma_f32 v[66:67], v[66:67], v[74:75], v[72:73]
	s_nop 0
	v_cvt_pk_bf16_f32 v72, v66, v67
	v_lshlrev_b32_e32 v66, 16, v149
	v_and_b32_e32 v67, 0xffff0000, v149
	v_pk_fma_f32 v[66:67], v[68:69], v[76:77], v[66:67]
	s_nop 0
	v_cvt_pk_bf16_f32 v73, v66, v67
	global_store_dwordx4 v[218:219], v[70:73], off offset:256
	v_add_u32_e32 v98, 0x80, v214
	v_ashrrev_i32_e32 v99, 31, v98
	v_lshlrev_b64 v[66:67], 12, v[98:99]
	v_lshl_add_u64 v[128:129], v[216:217], 0, v[66:67]
	v_lshlrev_b64 v[66:67], 12, v[214:215]
	v_lshl_add_u64 v[66:67], v[216:217], 0, v[66:67]
	s_mov_b64 s[14:15], 0x90000
	v_lshl_add_u64 v[126:127], v[66:67], 0, s[14:15]
	s_mov_b32 s14, 0x90000
	v_add_co_u32_e32 v68, vcc, s14, v66
	s_mov_b64 s[14:15], 0xa0000
	s_nop 0
	v_addc_co_u32_e32 v69, vcc, 0, v67, vcc
	v_lshl_add_u64 v[124:125], v[66:67], 0, s[14:15]
	s_mov_b32 s14, 0xa0000
	v_add_co_u32_e32 v70, vcc, s14, v66
	s_mov_b64 s[14:15], 0xb0000
	s_nop 0
	v_addc_co_u32_e32 v71, vcc, 0, v67, vcc
	v_lshl_add_u64 v[122:123], v[66:67], 0, s[14:15]
	v_add_co_u32_e32 v66, vcc, 0xb0000, v66
	global_load_dwordx4 v[94:97], v[128:129], off
	global_load_dwordx4 v[90:93], v[128:129], off offset:256
	v_addc_co_u32_e32 v67, vcc, 0, v67, vcc
	global_load_dwordx4 v[82:85], v[126:127], off offset:256
	global_load_dwordx4 v[74:77], v[124:125], off offset:256
	global_load_dwordx4 v[78:81], v[70:71], off
	s_nop 0
	global_load_dwordx4 v[70:73], v[66:67], off
	global_load_dwordx4 v[86:89], v[68:69], off
	s_nop 0
	global_load_dwordx4 v[66:69], v[122:123], off offset:256
	s_add_i32 s14, s16, 0xffff0080
	s_lshr_b32 s14, s14, 5
	s_add_i32 s14, s14, 32
	v_ashrrev_i32_e32 v132, 11, v98
	v_mov_b32_e32 v98, s14
	s_mov_b32 s14, 0xff80
	v_cmp_gt_i32_e32 vcc, s14, v214
	s_movk_i32 s14, 0x6000
	v_mov_b64_e32 v[106:107], v[118:119]
	v_cndmask_b32_e32 v100, v98, v132, vcc
	v_mov_b64_e32 v[98:99], s[6:7]
	v_mad_i64_i32 v[98:99], s[14:15], v100, s14, v[98:99]
	v_lshl_add_u64 v[130:131], v[212:213], 2, v[98:99]
	s_and_b64 vcc, exec, s[2:3]
	v_mov_b64_e32 v[108:109], v[120:121]
	s_cbranch_vccnz .LBB0_3118
	global_load_dwordx4 v[106:109], v[130:131], off

; __device__ __forceinline__ unsigned pk2(float lo, float hi) { const f32x2 v = {lo, hi}; const bf16v2_t b = __builtin_convertvector(v, bf16v2_t); return __builtin_bit_cast(unsigned, b); }
;     __device__ __forceinline__ void operator()(const f32x4 (&acc)[2][2][4][2], const pg8::Unit& u, int wr, int wc, int fr, int fq) const {
;     ...
; #pragma unroll
;                 for (int ai = 0; ai < 2; ++ai) {
;                     u32x4 xv[4][2];
; #pragma unroll
;                     for (int m = 0; m < 4; ++m)
; #pragma unroll
;                         for (int bj = 0; bj < 2; ++bj) xv[m][bj] = *(const u32x4*)(X16 + (size_t)(row0 + ai * 128 + m * 16) * XS + c0 + bj * 128);
; #pragma unroll
;                     for (int m = 0; m < 4; ++m) {
;                         const int row = row0 + ai * 128 + m * 16;
;                         const float* gp = gate + (size_t)seq_of(row) * 6144 + c0;
; #pragma unroll
;                         for (int bj = 0; bj < 2; ++bj) {
;                             const f32x4 g0 = uni ? gU[bj][0] : *(const f32x4*)(gp + bj * 128), g1 = uni ? gU[bj][1] : *(const f32x4*)(gp + bj * 128 + 4);
;                             float x[8]; unpack8(xv[m][bj], x);
;                             const f32x4 a0 = acc[ai][bj][m][0], a1 = acc[ai][bj][m][1];
;                             u32x4 w; w.x = pk2(x[0] + g0[0] * a0[0], x[1] + g0[1] * a0[1]); w.y = pk2(x[2] + g0[2] * a0[2], x[3] + g0[3] * a0[3]);
;                             w.z = pk2(x[4] + g1[0] * a1[0], x[5] + g1[1] * a1[1]); w.w = pk2(x[6] + g1[2] * a1[2], x[7] + g1[3] * a1[3]);
;                             *(u32x4*)(X16 + (size_t)row * XS + c0 + bj * 128) = w;
;                         }
;                     }
;                     __builtin_amdgcn_sched_barrier(0);
;                 }
.LBB0_3122:
	v_mov_b64_e32 v[58:59], v[102:103]
	s_and_b64 vcc, exec, s[2:3]
	v_mov_b64_e32 v[60:61], v[104:105]
	s_cbranch_vccnz .LBB0_3124
	global_load_dwordx4 v[58:61], v[130:131], off offset:528
	s_waitcnt vmcnt(0)
.LBB0_3124:
	v_lshlrev_b32_e32 v94, 16, v90
	v_and_b32_e32 v95, 0xffff0000, v90
	v_pk_fma_f32 v[54:55], v[54:55], v[62:63], v[94:95]
	v_lshlrev_b32_e32 v62, 16, v91
	v_and_b32_e32 v63, 0xffff0000, v91
	v_pk_fma_f32 v[56:57], v[56:57], v[64:65], v[62:63]
	v_cvt_pk_bf16_f32 v54, v54, v55
	v_cvt_pk_bf16_f32 v55, v56, v57
	v_lshlrev_b32_e32 v56, 16, v92
	v_and_b32_e32 v57, 0xffff0000, v92
	v_pk_fma_f32 v[50:51], v[50:51], v[58:59], v[56:57]
	s_add_i32 s14, s16, 0xffff0090
	v_cvt_pk_bf16_f32 v56, v50, v51
	v_lshlrev_b32_e32 v50, 16, v93
	v_and_b32_e32 v51, 0xffff0000, v93
	s_lshr_b32 s14, s14, 5
	v_pk_fma_f32 v[50:51], v[52:53], v[60:61], v[50:51]
	s_add_i32 s14, s14, 32
	v_cvt_pk_bf16_f32 v57, v50, v51
	v_mov_b32_e32 v50, s14
	s_mov_b32 s14, 0xff70
	v_cmp_gt_i32_e32 vcc, s14, v214
	s_movk_i32 s14, 0x6000
	global_store_dwordx4 v[128:129], v[54:57], off offset:256
	v_cndmask_b32_e32 v52, v50, v132, vcc
	v_mov_b64_e32 v[50:51], s[6:7]
	v_mad_i64_i32 v[50:51], s[14:15], v52, s14, v[50:51]
	v_mov_b64_e32 v[54:55], v[118:119]
	v_lshl_add_u64 v[58:59], v[212:213], 2, v[50:51]
	s_and_b64 vcc, exec, s[2:3]
	v_mov_b64_e32 v[56:57], v[120:121]
	s_cbranch_vccnz .LBB0_3126
	global_load_dwordx4 v[54:57], v[58:59], off
.LBB0_3126:
	v_mov_b64_e32 v[50:51], v[114:115]
	s_and_b64 vcc, exec, s[2:3]
	v_mov_b64_e32 v[52:53], v[116:117]
	s_cbranch_vccnz .LBB0_3128
	global_load_dwordx4 v[50:53], v[58:59], off offset:16
	s_waitcnt vmcnt(0)
.LBB0_3128:
	v_lshlrev_b32_e32 v60, 16, v86
	v_and_b32_e32 v61, 0xffff0000, v86
	v_pk_fma_f32 v[46:47], v[46:47], v[54:55], v[60:61]
	v_lshlrev_b32_e32 v54, 16, v87
	v_and_b32_e32 v55, 0xffff0000, v87
	v_pk_fma_f32 v[48:49], v[48:49], v[56:57], v[54:55]
	v_cvt_pk_bf16_f32 v46, v46, v47
	v_cvt_pk_bf16_f32 v47, v48, v49
	v_lshlrev_b32_e32 v48, 16, v88
	v_and_b32_e32 v49, 0xffff0000, v88
	v_pk_fma_f32 v[42:43], v[42:43], v[50:51], v[48:49]
	s_and_b64 vcc, exec, s[2:3]
	v_cvt_pk_bf16_f32 v48, v42, v43
	v_lshlrev_b32_e32 v42, 16, v89
	v_and_b32_e32 v43, 0xffff0000, v89
	v_pk_fma_f32 v[42:43], v[44:45], v[52:53], v[42:43]
	s_nop 0
	v_cvt_pk_bf16_f32 v49, v42, v43
	global_store_dwordx4 v[126:127], v[46:49], off
	s_nop 1
	v_mov_b64_e32 v[46:47], v[110:111]
	v_mov_b64_e32 v[48:49], v[112:113]
	s_cbranch_vccnz .LBB0_3130
	global_load_dwordx4 v[46:49], v[58:59], off offset:512
.LBB0_3130:
	v_mov_b64_e32 v[42:43], v[102:103]
	s_and_b64 vcc, exec, s[2:3]
	v_mov_b64_e32 v[44:45], v[104:105]
	s_cbranch_vccnz .LBB0_3132
	global_load_dwordx4 v[42:45], v[58:59], off offset:528
	s_waitcnt vmcnt(0)
.LBB0_3132:
	v_lshlrev_b32_e32 v50, 16, v82
	v_and_b32_e32 v51, 0xffff0000, v82
	v_pk_fma_f32 v[38:39], v[38:39], v[46:47], v[50:51]
	v_lshlrev_b32_e32 v46, 16, v83
	v_and_b32_e32 v47, 0xffff0000, v83
	v_pk_fma_f32 v[40:41], v[40:41], v[48:49], v[46:47]
	v_cvt_pk_bf16_f32 v38, v38, v39
	v_cvt_pk_bf16_f32 v39, v40, v41
	v_lshlrev_b32_e32 v40, 16, v84
	v_and_b32_e32 v41, 0xffff0000, v84
	v_pk_fma_f32 v[34:35], v[34:35], v[42:43], v[40:41]
	s_add_i32 s14, s16, 0xffff00a0
	v_cvt_pk_bf16_f32 v40, v34, v35
	v_lshlrev_b32_e32 v34, 16, v85
	v_and_b32_e32 v35, 0xffff0000, v85
	s_lshr_b32 s14, s14, 5
	v_pk_fma_f32 v[34:35], v[36:37], v[44:45], v[34:35]
	s_add_i32 s14, s14, 32
	v_cvt_pk_bf16_f32 v41, v34, v35
	v_mov_b32_e32 v34, s14
	s_mov_b32 s14, 0xff60
	v_cmp_gt_i32_e32 vcc, s14, v214
	s_movk_i32 s14, 0x6000
	global_store_dwordx4 v[126:127], v[38:41], off offset:256
	v_cndmask_b32_e32 v36, v34, v132, vcc
	v_mov_b64_e32 v[34:35], s[6:7]
	v_mad_i64_i32 v[34:35], s[14:15], v36, s14, v[34:35]
	v_mov_b64_e32 v[38:39], v[118:119]
	v_lshl_add_u64 v[42:43], v[212:213], 2, v[34:35]
	s_and_b64 vcc, exec, s[2:3]
	v_mov_b64_e32 v[40:41], v[120:121]
	s_cbranch_vccnz .LBB0_3134
	global_load_dwordx4 v[38:41], v[42:43], off
.LBB0_3134:
	v_mov_b64_e32 v[34:35], v[114:115]
	s_and_b64 vcc, exec, s[2:3]
	v_mov_b64_e32 v[36:37], v[116:117]
	s_cbranch_vccnz .LBB0_3136
	global_load_dwordx4 v[34:37], v[42:43], off offset:16
	s_waitcnt vmcnt(0)
; __device__ __forceinline__ unsigned pk2(float lo, float hi) { const f32x2 v = {lo, hi}; const bf16v2_t b = __builtin_convertvector(v, bf16v2_t); return __builtin_bit_cast(unsigned, b); }
;     __device__ __forceinline__ void operator()(const f32x4 (&acc)[2][2][4][2], const pg8::Unit& u, int wr, int wc, int fr, int fq) const {
;     ...
; #pragma unroll
;                 for (int ai = 0; ai < 2; ++ai) {
;                     u32x4 xv[4][2];
; #pragma unroll
;                     for (int m = 0; m < 4; ++m)
; #pragma unroll
;                         for (int bj = 0; bj < 2; ++bj) xv[m][bj] = *(const u32x4*)(X16 + (size_t)(row0 + ai * 128 + m * 16) * XS + c0 + bj * 128);
; #pragma unroll
;                     for (int m = 0; m < 4; ++m) {
;                         const int row = row0 + ai * 128 + m * 16;
;                         const float* gp = gate + (size_t)seq_of(row) * 6144 + c0;
; #pragma unroll
;                         for (int bj = 0; bj < 2; ++bj) {
;                             const f32x4 g0 = uni ? gU[bj][0] : *(const f32x4*)(gp + bj * 128), g1 = uni ? gU[bj][1] : *(const f32x4*)(gp + bj * 128 + 4);
;                             float x[8]; unpack8(xv[m][bj], x);
;                             const f32x4 a0 = acc[ai][bj][m][0], a1 = acc[ai][bj][m][1];
;                             u32x4 w; w.x = pk2(x[0] + g0[0] * a0[0], x[1] + g0[1] * a0[1]); w.y = pk2(x[2] + g0[2] * a0[2], x[3] + g0[3] * a0[3]);
;                             w.z = pk2(x[4] + g1[0] * a1[0], x[5] + g1[1] * a1[1]); w.w = pk2(x[6] + g1[2] * a1[2], x[7] + g1[3] * a1[3]);
;                             *(u32x4*)(X16 + (size_t)row * XS + c0 + bj * 128) = w;
;                         }
;                     }
;                     __builtin_amdgcn_sched_barrier(0);
;                 }
.LBB0_3136:
	v_lshlrev_b32_e32 v44, 16, v78
	v_and_b32_e32 v45, 0xffff0000, v78
	v_pk_fma_f32 v[30:31], v[30:31], v[38:39], v[44:45]
	v_lshlrev_b32_e32 v38, 16, v79
	v_and_b32_e32 v39, 0xffff0000, v79
	v_pk_fma_f32 v[32:33], v[32:33], v[40:41], v[38:39]
	v_cvt_pk_bf16_f32 v30, v30, v31
	v_cvt_pk_bf16_f32 v31, v32, v33
	v_lshlrev_b32_e32 v32, 16, v80
	v_and_b32_e32 v33, 0xffff0000, v80
	v_pk_fma_f32 v[26:27], v[26:27], v[34:35], v[32:33]
	s_and_b64 vcc, exec, s[2:3]
	v_cvt_pk_bf16_f32 v32, v26, v27
	v_lshlrev_b32_e32 v26, 16, v81
	v_and_b32_e32 v27, 0xffff0000, v81
	v_pk_fma_f32 v[26:27], v[28:29], v[36:37], v[26:27]
	s_nop 0
	v_cvt_pk_bf16_f32 v33, v26, v27
	global_store_dwordx4 v[124:125], v[30:33], off
	s_nop 1
	v_mov_b64_e32 v[30:31], v[110:111]
	v_mov_b64_e32 v[32:33], v[112:113]
	s_cbranch_vccnz .LBB0_3138
	global_load_dwordx4 v[30:33], v[42:43], off offset:512
.LBB0_3138:
	v_mov_b64_e32 v[26:27], v[102:103]
	s_and_b64 vcc, exec, s[2:3]
	v_mov_b64_e32 v[28:29], v[104:105]
	s_cbranch_vccnz .LBB0_3140
	global_load_dwordx4 v[26:29], v[42:43], off offset:528
	s_waitcnt vmcnt(0)
.LBB0_3140:
	v_lshlrev_b32_e32 v34, 16, v74
	v_and_b32_e32 v35, 0xffff0000, v74
	v_pk_fma_f32 v[22:23], v[22:23], v[30:31], v[34:35]
	v_lshlrev_b32_e32 v30, 16, v75
	v_and_b32_e32 v31, 0xffff0000, v75
	v_pk_fma_f32 v[24:25], v[24:25], v[32:33], v[30:31]
	v_cvt_pk_bf16_f32 v22, v22, v23
	v_cvt_pk_bf16_f32 v23, v24, v25
	v_lshlrev_b32_e32 v24, 16, v76
	v_and_b32_e32 v25, 0xffff0000, v76
	v_pk_fma_f32 v[18:19], v[18:19], v[26:27], v[24:25]
	s_add_i32 s16, s16, 0xffff00b0
	v_cvt_pk_bf16_f32 v24, v18, v19
	v_lshlrev_b32_e32 v18, 16, v77
	v_and_b32_e32 v19, 0xffff0000, v77
	s_lshr_b32 s14, s16, 5
	v_pk_fma_f32 v[18:19], v[20:21], v[28:29], v[18:19]
	s_add_i32 s14, s14, 32
	v_cvt_pk_bf16_f32 v25, v18, v19
	v_mov_b32_e32 v18, s14
	s_mov_b32 s14, 0xff50
	v_cmp_gt_i32_e32 vcc, s14, v214
	s_movk_i32 s14, 0x6000
	global_store_dwordx4 v[124:125], v[22:25], off offset:256
	v_cndmask_b32_e32 v20, v18, v132, vcc
	v_mov_b64_e32 v[18:19], s[6:7]
	v_mad_i64_i32 v[18:19], s[14:15], v20, s14, v[18:19]
	s_and_b64 vcc, exec, s[2:3]
	v_lshl_add_u64 v[18:19], v[212:213], 2, v[18:19]
	s_cbranch_vccnz .LBB0_3142
	global_load_dwordx4 v[118:121], v[18:19], off
.LBB0_3142:
	s_and_b64 vcc, exec, s[2:3]
	s_cbranch_vccnz .LBB0_3144
	global_load_dwordx4 v[114:117], v[18:19], off offset:16
	s_waitcnt vmcnt(0)
.LBB0_3144:
	v_lshlrev_b32_e32 v20, 16, v70
	v_and_b32_e32 v21, 0xffff0000, v70
	v_pk_fma_f32 v[14:15], v[14:15], v[118:119], v[20:21]
	v_lshlrev_b32_e32 v20, 16, v71
	v_and_b32_e32 v21, 0xffff0000, v71
	v_pk_fma_f32 v[16:17], v[16:17], v[120:121], v[20:21]
	v_cvt_pk_bf16_f32 v14, v14, v15
	v_cvt_pk_bf16_f32 v15, v16, v17
	v_lshlrev_b32_e32 v16, 16, v72
	v_and_b32_e32 v17, 0xffff0000, v72
	v_pk_fma_f32 v[10:11], v[10:11], v[114:115], v[16:17]
	s_and_b64 vcc, exec, s[2:3]
	v_cvt_pk_bf16_f32 v16, v10, v11
	v_lshlrev_b32_e32 v10, 16, v73
	v_and_b32_e32 v11, 0xffff0000, v73
	v_pk_fma_f32 v[10:11], v[12:13], v[116:117], v[10:11]
	s_nop 0
	v_cvt_pk_bf16_f32 v17, v10, v11
	global_store_dwordx4 v[122:123], v[14:17], off
	s_cbranch_vccnz .LBB0_3146
	global_load_dwordx4 v[110:113], v[18:19], off offset:512
.LBB0_3146:
	s_and_b64 vcc, exec, s[2:3]
	s_cbranch_vccnz .LBB0_3148
	global_load_dwordx4 v[102:105], v[18:19], off offset:528
	s_waitcnt vmcnt(0)
.LBB0_3148:
	v_lshlrev_b32_e32 v10, 16, v66
	v_and_b32_e32 v11, 0xffff0000, v66
	v_pk_fma_f32 v[6:7], v[6:7], v[110:111], v[10:11]
	v_lshlrev_b32_e32 v10, 16, v67
	v_and_b32_e32 v11, 0xffff0000, v67
	v_pk_fma_f32 v[8:9], v[8:9], v[112:113], v[10:11]
	v_cvt_pk_bf16_f32 v6, v6, v7
	v_cvt_pk_bf16_f32 v7, v8, v9
	v_lshlrev_b32_e32 v8, 16, v68
	v_and_b32_e32 v9, 0xffff0000, v68
	v_pk_fma_f32 v[2:3], v[2:3], v[102:103], v[8:9]
	s_nop 0
	v_cvt_pk_bf16_f32 v8, v2, v3
	v_lshlrev_b32_e32 v2, 16, v69
	v_and_b32_e32 v3, 0xffff0000, v69
	v_pk_fma_f32 v[2:3], v[4:5], v[104:105], v[2:3]
	s_nop 0
	v_cvt_pk_bf16_f32 v9, v2, v3
	global_store_dwordx4 v[122:123], v[6:9], off offset:256
	s_and_b64 vcc, exec, s[0:1]
	s_mov_b64 s[0:1], -1
	s_cbranch_vccnz .LBB0_3069
	s_andn2_b64 vcc, exec, s[4:5]
	s_cbranch_vccnz .LBB0_3068
	s_barrier
	s_branch .LBB0_3068
